# scan diagonal mask: valid = (le XNOR dir0) | eq, dropping the s_andn2 (eq is a subset of le), 60 sequences one SALU shorter; on top of v064
# speedup vs baseline: 1.0013x; 1.0013x over previous
; template <int MODE> __device__ __forceinline__ void ssd_scan_phase(Frame& F, int j, bool ctx_out) {
;     ...
;                 bf16x8 hf[2][4];
; #pragma unroll
;                 for (int pt = 0; pt < 2; ++pt)
; #pragma unroll
;                     for (int q = 0; q < 4; ++q) { const f32x4 lo4 = hT[2 * q][pt], hi4 = hT[2 * q + 1][pt]; u32x4 o; o.x = cvt_pk_bf16(lo4[0], lo4[1]); o.y = cvt_pk_bf16(lo4[2], lo4[3]); o.z = cvt_pk_bf16(hi4[0], hi4[1]); o.w = cvt_pk_bf16(hi4[2], hi4[3]);
;                         hf[pt][q] = __builtin_bit_cast(bf16x8, o); }
;                 bf16x8 xb_cur = xf[1][0], xb_nxt = xf[1][0];
; #pragma unroll 8
;                 for (int lt = 0; lt < 8; ++lt) {
;                     const int l = 16 * lt + fr; const float cl = tab[l];
;                     f32x4 accd[2], acco[2];
;                     accd[0] = accd[1] = acco[0] = acco[1] = (f32x4){0.f, 0.f, 0.f, 0.f};
;                     const int kd = lt >> 1;
;                     if ((lt & 1) == 0) { xb_cur = xb_nxt; if (kd + 1 < 4) xb_nxt = *(const bf16x8*)(xl + (size_t)16 * T + 32 * (kd + 1)); }
;                     const bf16x8 xa = xf[0][kd], xb = xb_cur;
; #pragma unroll
;                     for (int ks = 0; ks < 4; ++ks) {
;                         const bool full = dir == 0 ? (ks < kd) : (ks > kd);
;                         if (full) {
;                             const bf16x8 gf = *(const LAS bf16x8*)(GS + l * 256 + (((4 * ks + fq) ^ fr) << 4));
;                             const float f1 = __builtin_amdgcn_exp2f(cl - tab[dir == 0 ? 32 * ks + 31 : 32 * ks]);
;                             const f32x4 z4 = (f32x4){0.f, 0.f, 0.f, 0.f};
;                             const f32x4 t0 = __builtin_amdgcn_mfma_f32_16x16x32_bf16(xs2[0][ks], gf, z4, 0, 0, 0), t1 = __builtin_amdgcn_mfma_f32_16x16x32_bf16(xs2[1][ks], gf, z4, 0, 0, 0);
;                             accd[0] += t0 * f1; accd[1] += t1 * f1;
;                         }
;                     }
; #pragma unroll
;                     for (int q = 0; q < 4; ++q) {
;                         const u32x2 lo = *(const LAS u32x2*)(CS + l * 256 + (((4 * q + (fq >> 1)) ^ fr) << 4) + (fq & 1) * 8), hi = *(const LAS u32x2*)(CS + l * 256 + (((4 * q + 2 + (fq >> 1)) ^ fr) << 4) + (fq & 1) * 8);
;                         u32x4 c4; c4.x = lo.x; c4.y = lo.y; c4.z = hi.x; c4.w = hi.y; const bf16x8 cfr = __builtin_bit_cast(bf16x8, c4);
.LBB0_494:
	v_add_u32_e32 v122, 2, v165
	v_xor_b32_e32 v123, v165, v176
	v_xor_b32_e32 v122, v122, v176
	v_add3_u32 v167, 0, v132, v195
	v_lshlrev_b32_e32 v185, 4, v123
	v_lshlrev_b32_e32 v183, 4, v122
	v_add_u32_e32 v123, v167, v185
	v_add_u32_e32 v122, v167, v183
	v_cvt_pk_bf16_f32 v116, v0, v1
	v_cvt_pk_bf16_f32 v117, v2, v3
	v_cvt_pk_bf16_f32 v118, v12, v13
	v_cvt_pk_bf16_f32 v119, v14, v15
	v_cvt_pk_bf16_f32 v124, v4, v5
	v_cvt_pk_bf16_f32 v125, v6, v7
	v_cvt_pk_bf16_f32 v126, v16, v17
	v_cvt_pk_bf16_f32 v127, v18, v19
	ds_read_b64 v[160:161], v123
	ds_read_b64 v[162:163], v122
	v_add_u32_e32 v122, 4, v165
	v_add_u32_e32 v129, 6, v165
	v_xor_b32_e32 v122, v122, v176
	v_xor_b32_e32 v129, v129, v176
	v_lshlrev_b32_e32 v187, 4, v122
	v_lshlrev_b32_e32 v213, 4, v129
	v_add_u32_e32 v122, v167, v187
	v_add_u32_e32 v129, v167, v213
	v_cvt_pk_bf16_f32 v112, v20, v21
	v_cvt_pk_bf16_f32 v113, v22, v23
	v_cvt_pk_bf16_f32 v114, v28, v29
	v_cvt_pk_bf16_f32 v115, v30, v31
	v_cvt_pk_bf16_f32 v120, v24, v25
	v_cvt_pk_bf16_f32 v121, v26, v27
	ds_read_b64 v[132:133], v122
	ds_read_b32 v217, v214 offset:64
	v_cvt_pk_bf16_f32 v122, v32, v33
	v_cvt_pk_bf16_f32 v123, v34, v35
	ds_read_b64 v[134:135], v129
	v_add_u32_e32 v129, 8, v165
	v_add_u32_e32 v130, 10, v165
	v_add_u32_e32 v131, 12, v165
	s_waitcnt lgkmcnt(0)
	v_mfma_f32_16x16x32_bf16 v[168:171], v[116:119], v[160:163], 0
	v_xor_b32_e32 v129, v129, v176
	v_xor_b32_e32 v130, v130, v176
	v_xor_b32_e32 v131, v131, v176
	v_mfma_f32_16x16x32_bf16 v[160:163], v[124:127], v[160:163], 0
	v_lshlrev_b32_e32 v212, 4, v129
	v_lshlrev_b32_e32 v211, 4, v130
	v_lshlrev_b32_e32 v191, 4, v131
	v_add_u32_e32 v129, v167, v212
	v_add_u32_e32 v130, v167, v211
	v_add_u32_e32 v131, v167, v191
	v_cvt_pk_bf16_f32 v108, v36, v37
	v_cvt_pk_bf16_f32 v109, v38, v39
	v_cvt_pk_bf16_f32 v110, v52, v53
	v_cvt_pk_bf16_f32 v111, v54, v55
	v_cvt_pk_bf16_f32 v128, v40, v41
	ds_read_b64 v[172:173], v129
	ds_read_b64 v[174:175], v130
	ds_read_b64 v[218:219], v131
	v_cvt_pk_bf16_f32 v129, v42, v43
	v_cvt_pk_bf16_f32 v130, v56, v57
	v_cvt_pk_bf16_f32 v131, v58, v59
	v_mfma_f32_16x16x32_bf16 v[168:171], v[112:115], v[132:135], v[168:171]
	v_lshlrev_b32_e32 v215, 4, v208
	v_cvt_pk_bf16_f32 v104, v60, v61
	v_cvt_pk_bf16_f32 v105, v62, v63
	v_mfma_f32_16x16x32_bf16 v[160:163], v[120:123], v[132:135], v[160:163]
	v_add_u32_e32 v135, 14, v165
	v_xor_b32_e32 v135, v135, v176
	v_lshlrev_b32_e32 v210, 4, v135
	s_waitcnt lgkmcnt(0)
	v_mfma_f32_16x16x32_bf16 v[168:171], v[108:111], v[172:175], v[168:171]
	v_add_u32_e32 v135, v167, v210
	v_cvt_pk_bf16_f32 v106, v68, v69
	v_cvt_pk_bf16_f32 v107, v70, v71
	v_mfma_f32_16x16x32_bf16 v[160:163], v[128:131], v[172:175], v[160:163]
	v_lshlrev_b32_e32 v172, 2, v164
	v_add_u32_e32 v164, v166, v215
	v_cvt_pk_bf16_f32 v132, v64, v65
	v_cvt_pk_bf16_f32 v133, v66, v67
	v_cvt_pk_bf16_f32 v134, v72, v73
	ds_read_b64 v[220:221], v135
	v_cvt_pk_bf16_f32 v135, v74, v75
	ds_read_b128 v[164:167], v164
	v_ashrrev_i32_e32 v173, 31, v172
	s_waitcnt lgkmcnt(0)
	v_mfma_f32_16x16x32_bf16 v[226:229], v[104:107], v[218:221], v[168:171]
	v_lshl_add_u64 v[198:199], v[172:173], 1, s[0:1]
	v_lshlrev_b32_e32 v222, 16, v166
	v_and_b32_e32 v223, 0xffff0000, v166
	v_mfma_f32_16x16x32_bf16 v[230:233], v[132:135], v[218:221], v[160:163]
	v_lshlrev_b32_e32 v218, 16, v164
	v_and_b32_e32 v219, 0xffff0000, v164
	v_lshlrev_b32_e32 v220, 16, v165
	v_and_b32_e32 v221, 0xffff0000, v165
	v_lshlrev_b32_e32 v224, 16, v167
	v_and_b32_e32 v225, 0xffff0000, v167
	ds_read_b128 v[172:175], v197
	ds_read_b128 v[164:167], v197 offset:16
	ds_read_b128 v[168:171], v197 offset:512
	ds_read_b128 v[160:163], v197 offset:528
	v_cmp_le_i32_e32 vcc, v180, v176
	s_waitcnt lgkmcnt(0)
; #define LAS __attribute__((address_space(3)))
; __device__ __forceinline__ unsigned cvt_pk_bf16(float lo, float hi) { const f32x2 v = {lo, hi}; return __builtin_bit_cast(unsigned, __builtin_convertvector(v, bf16x2_t)); }
; __device__ __forceinline__ u32x4 pack8(const float (&f)[8]) { u32x4 w; w.x = cvt_pk_bf16(f[0], f[1]); w.y = cvt_pk_bf16(f[2], f[3]); w.z = cvt_pk_bf16(f[4], f[5]); w.w = cvt_pk_bf16(f[6], f[7]); return w; }
; template <int MODE> __device__ __forceinline__ void ssd_scan_phase(Frame& F, int j, bool ctx_out) {
;     ...
;                         float gg[8]; unpack8(*(const LAS u32x4*)(GS + l * 256 + (((4 * kd + fq) ^ fr) << 4)), gg);
;                         const f32x4 ca = *(const LAS f32x4*)(tab + 32 * kd + 8 * fq), cb = *(const LAS f32x4*)(tab + 32 * kd + 8 * fq + 4);
;                         const f32x4 da = *(const LAS f32x4*)(tab + 128 + 32 * kd + 8 * fq), db = *(const LAS f32x4*)(tab + 128 + 32 * kd + 8 * fq + 4);
;                         const float cs[8] = {ca.x, ca.y, ca.z, ca.w, cb.x, cb.y, cb.z, cb.w}, ds[8] = {da.x, da.y, da.z, da.w, db.x, db.y, db.z, db.w};
;                         float m[8];
; #pragma unroll
;                         for (int jj = 0; jj < 8; ++jj) { const int s = 32 * kd + 8 * fq + jj; const bool valid = dir == 0 ? (s <= l) : (s >= l);
;                             const float e = valid ? __builtin_amdgcn_exp2f(cl - cs[jj]) : 0.f; m[jj] = gg[jj] * e * ds[jj]; if (dir == 0 && s == l) m[jj] += dsk; }
;                         const bf16x8 mf = __builtin_bit_cast(bf16x8, pack8(m));
;                         accd[0] = __builtin_amdgcn_mfma_f32_16x16x32_bf16(xa, mf, accd[0], 0, 0, 0);
;                         accd[1] = __builtin_amdgcn_mfma_f32_16x16x32_bf16(xb, mf, accd[1], 0, 0, 0);
;                     }
;                     const float el = __builtin_amdgcn_exp2f(cl);
; #pragma unroll
;                     for (int pt = 0; pt < 2; ++pt) { const f32x4 y = accd[pt] + acco[pt] * el; u32x2 o; o.x = cvt_pk_bf16(y[0], y[1]); o.y = cvt_pk_bf16(y[2], y[3]);
;                         *(u32x2*)(yout + (size_t)(row0 + l) * DI + h * 64 + ph * 32 + 16 * pt + 4 * fq) = o; }
	v_sub_f32_e32 v236, v216, v172
	v_exp_f32_e32 v236, v236
	v_cndmask_b32_e64 v234, 0, 1, vcc
	v_cmp_ge_i32_e32 vcc, v180, v176
	s_add_i32 s5, s5, s40
	v_sub_f32_e32 v237, v216, v173
	v_cndmask_b32_e64 v235, 0, 1, vcc
	v_cndmask_b32_e64 v234, v235, v234, s[38:39]
	v_and_b32_e32 v234, 1, v234
	v_cmp_eq_u32_e64 s[40:41], 1, v234
	v_cmp_eq_u32_e32 vcc, v180, v176
	s_and_b64 s[42:43], s[38:39], vcc
	v_cndmask_b32_e64 v234, 0, v236, s[40:41]
	v_mul_f32_e32 v218, v234, v218
	v_mul_f32_e32 v234, v168, v218
	v_fma_f32 v218, v168, v218, v203
	v_cndmask_b32_e64 v234, v234, v218, s[42:43]
	v_or_b32_e32 v218, 1, v180
	v_exp_f32_e32 v237, v237
	v_sub_f32_e32 v246, v216, v174
	v_exp_f32_e32 v246, v246
	v_sub_f32_e32 v247, v216, v175
	v_cmp_lt_i32_e32 vcc, v180, v176
	v_cmp_eq_u32_e64 s[100:101], v218, v176
	s_xnor_b64 vcc, vcc, s[38:39]
	s_or_b64 vcc, vcc, s[100:101]
	v_exp_f32_e32 v247, v247
	v_sub_f32_e32 v248, v216, v164
	v_cndmask_b32_e32 v235, 0, v237, vcc
	v_mul_f32_e32 v219, v235, v219
	v_cmp_eq_u32_e32 vcc, v218, v176
	v_mul_f32_e32 v235, v169, v219
	v_fma_f32 v219, v169, v219, v203
	s_and_b64 vcc, s[38:39], vcc
	v_cndmask_b32_e32 v235, v235, v219, vcc
	v_or_b32_e32 v219, 2, v180
	v_exp_f32_e32 v248, v248
	v_sub_f32_e32 v249, v216, v165
	v_exp_f32_e32 v249, v249
	v_sub_f32_e32 v240, v216, v166
	v_cmp_le_i32_e32 vcc, v219, v176
	v_cmp_eq_u32_e64 s[100:101], v219, v176
	s_xnor_b64 vcc, vcc, s[38:39]
	s_or_b64 vcc, vcc, s[100:101]
	v_exp_f32_e32 v240, v240
	v_sub_f32_e32 v178, v216, v167
	v_cndmask_b32_e32 v236, 0, v246, vcc
	v_mul_f32_e32 v220, v236, v220
	v_cmp_eq_u32_e32 vcc, v219, v176
	v_mul_f32_e32 v236, v170, v220
	v_fma_f32 v220, v170, v220, v203
	s_and_b64 vcc, s[38:39], vcc
	v_cndmask_b32_e32 v236, v236, v220, vcc
	v_or_b32_e32 v220, 3, v180
	v_exp_f32_e32 v178, v178
	v_cvt_pk_bf16_f32 v234, v234, v235
	v_exp_f32_e32 v216, v216
	s_mov_b32 s94, s92
	v_cmp_le_i32_e32 vcc, v220, v176
	v_cmp_eq_u32_e64 s[100:101], v220, v176
	s_xnor_b64 vcc, vcc, s[38:39]
	s_or_b64 vcc, vcc, s[100:101]
	s_mov_b32 s95, s92
	s_mov_b32 s93, s92
	v_cndmask_b32_e32 v237, 0, v247, vcc
	v_mul_f32_e32 v221, v237, v221
	v_cmp_eq_u32_e32 vcc, v220, v176
	v_mul_f32_e32 v237, v171, v221
	v_fma_f32 v221, v171, v221, v203
	s_and_b64 vcc, s[38:39], vcc
	v_cndmask_b32_e32 v237, v237, v221, vcc
	v_or_b32_e32 v221, 4, v180
	v_cvt_pk_bf16_f32 v235, v236, v237
	s_nop 0
	s_nop 1
	v_cmp_le_i32_e32 vcc, v221, v176
	v_cmp_eq_u32_e64 s[100:101], v221, v176
	s_xnor_b64 vcc, vcc, s[38:39]
	s_or_b64 vcc, vcc, s[100:101]
	v_cndmask_b32_e32 v246, 0, v248, vcc
	v_mul_f32_e32 v222, v246, v222
	v_cmp_eq_u32_e32 vcc, v221, v176
	v_mul_f32_e32 v246, v160, v222
	v_fma_f32 v222, v160, v222, v203
	s_and_b64 vcc, s[38:39], vcc
	v_cndmask_b32_e32 v246, v246, v222, vcc
	v_or_b32_e32 v222, 5, v180
	s_nop 1
	s_nop 1
	v_cmp_le_i32_e32 vcc, v222, v176
	v_cmp_eq_u32_e64 s[100:101], v222, v176
	s_xnor_b64 vcc, vcc, s[38:39]
	s_or_b64 vcc, vcc, s[100:101]
	v_cndmask_b32_e32 v247, 0, v249, vcc
	v_mul_f32_e32 v223, v247, v223
	v_cmp_eq_u32_e32 vcc, v222, v176
	v_mul_f32_e32 v247, v161, v223
	v_fma_f32 v223, v161, v223, v203
	s_and_b64 vcc, s[38:39], vcc
	v_cndmask_b32_e32 v247, v247, v223, vcc
	v_or_b32_e32 v223, 6, v180
	v_cvt_pk_bf16_f32 v236, v246, v247
	s_nop 0
	s_nop 1
	v_cmp_le_i32_e32 vcc, v223, v176
	v_cmp_eq_u32_e64 s[100:101], v223, v176
	s_xnor_b64 vcc, vcc, s[38:39]
	s_or_b64 vcc, vcc, s[100:101]
	v_cndmask_b32_e32 v240, 0, v240, vcc
	v_mul_f32_e32 v224, v240, v224
	v_cmp_eq_u32_e32 vcc, v223, v176
	v_mul_f32_e32 v240, v162, v224
	v_fma_f32 v224, v162, v224, v203
	s_and_b64 vcc, s[38:39], vcc
	v_cndmask_b32_e32 v240, v240, v224, vcc
	v_or_b32_e32 v224, 7, v180
	s_nop 1
	s_nop 1
	v_cmp_le_i32_e32 vcc, v224, v176
	v_cmp_eq_u32_e64 s[100:101], v224, v176
	s_xnor_b64 vcc, vcc, s[38:39]
	s_or_b64 vcc, vcc, s[100:101]
	v_cndmask_b32_e32 v178, 0, v178, vcc
	v_mul_f32_e32 v178, v178, v225
	v_cmp_eq_u32_e32 vcc, v224, v176
	v_mul_f32_e32 v179, v163, v178
	v_fma_f32 v178, v163, v178, v203
	s_and_b64 vcc, s[38:39], vcc
	v_cndmask_b32_e32 v178, v179, v178, vcc
	v_cvt_pk_bf16_f32 v237, v240, v178
	s_and_b64 vcc, exec, s[44:45]
	s_nop 0
	v_mfma_f32_16x16x32_bf16 v[246:249], v[140:143], v[234:237], v[156:159]
	v_mfma_f32_16x16x32_bf16 v[152:155], v[144:147], v[234:237], v[152:155]
	v_add_u32_e32 v234, s5, v176
	v_ashrrev_i32_e32 v235, 31, v234
	v_lshlrev_b64 v[234:235], 13, v[234:235]
	s_nop 3
	v_pk_fma_f32 v[228:229], v[216:217], v[228:229], v[248:249] op_sel_hi:[0,1,1]
	v_pk_fma_f32 v[226:227], v[216:217], v[226:227], v[246:247] op_sel_hi:[0,1,1]
	v_pk_fma_f32 v[154:155], v[216:217], v[232:233], v[154:155] op_sel_hi:[0,1,1]
	v_pk_fma_f32 v[152:153], v[216:217], v[230:231], v[152:153] op_sel_hi:[0,1,1]
	v_lshl_add_u64 v[234:235], v[198:199], 0, v[234:235]
	v_cvt_pk_bf16_f32 v226, v226, v227
	v_cvt_pk_bf16_f32 v227, v228, v229
	v_cvt_pk_bf16_f32 v152, v152, v153
	v_cvt_pk_bf16_f32 v153, v154, v155
	v_or_b32_e32 v216, 16, v176
	v_mov_b64_e32 v[158:159], s[94:95]
	global_store_dwordx2 v[234:235], v[226:227], off
	global_store_dwordx2 v[234:235], v[152:153], off offset:32
	v_lshlrev_b32_e32 v226, 8, v216
	v_mov_b64_e32 v[154:155], s[94:95]
	v_mov_b64_e32 v[156:157], s[92:93]
	v_add_u32_e32 v225, s87, v226
	v_mov_b64_e32 v[152:153], s[92:93]
	s_cbranch_vccz .LBB0_526
	s_and_b64 vcc, exec, s[44:45]
	s_cbranch_vccz .LBB0_527

; template <int MODE> __device__ __forceinline__ void ssd_scan_phase(Frame& F, int j, bool ctx_out) {
;     ...
;                 for (int lt = 0; lt < 8; ++lt) {
;                     const int l = 16 * lt + fr; const float cl = tab[l];
;                     f32x4 accd[2], acco[2];
;                     accd[0] = accd[1] = acco[0] = acco[1] = (f32x4){0.f, 0.f, 0.f, 0.f};
;                     const int kd = lt >> 1;
;                     if ((lt & 1) == 0) { xb_cur = xb_nxt; if (kd + 1 < 4) xb_nxt = *(const bf16x8*)(xl + (size_t)16 * T + 32 * (kd + 1)); }
;                     const bf16x8 xa = xf[0][kd], xb = xb_cur;
; #pragma unroll
;                     for (int ks = 0; ks < 4; ++ks) {
;                         const bool full = dir == 0 ? (ks < kd) : (ks > kd);
;                         if (full) {
;                             const bf16x8 gf = *(const LAS bf16x8*)(GS + l * 256 + (((4 * ks + fq) ^ fr) << 4));
;                             const float f1 = __builtin_amdgcn_exp2f(cl - tab[dir == 0 ? 32 * ks + 31 : 32 * ks]);
;                             const f32x4 z4 = (f32x4){0.f, 0.f, 0.f, 0.f};
;                             const f32x4 t0 = __builtin_amdgcn_mfma_f32_16x16x32_bf16(xs2[0][ks], gf, z4, 0, 0, 0), t1 = __builtin_amdgcn_mfma_f32_16x16x32_bf16(xs2[1][ks], gf, z4, 0, 0, 0);
;                             accd[0] += t0 * f1; accd[1] += t1 * f1;
;                         }
;                     }
; #pragma unroll
;                     for (int q = 0; q < 4; ++q) {
;                         const u32x2 lo = *(const LAS u32x2*)(CS + l * 256 + (((4 * q + (fq >> 1)) ^ fr) << 4) + (fq & 1) * 8), hi = *(const LAS u32x2*)(CS + l * 256 + (((4 * q + 2 + (fq >> 1)) ^ fr) << 4) + (fq & 1) * 8);
;                         u32x4 c4; c4.x = lo.x; c4.y = lo.y; c4.z = hi.x; c4.w = hi.y; const bf16x8 cfr = __builtin_bit_cast(bf16x8, c4);
;                         acco[0] = __builtin_amdgcn_mfma_f32_16x16x32_bf16(hf[0][q], cfr, acco[0], 0, 0, 0);
;                         acco[1] = __builtin_amdgcn_mfma_f32_16x16x32_bf16(hf[1][q], cfr, acco[1], 0, 0, 0);
;                     }
;                     {
;                         float gg[8]; unpack8(*(const LAS u32x4*)(GS + l * 256 + (((4 * kd + fq) ^ fr) << 4)), gg);
;                         const f32x4 ca = *(const LAS f32x4*)(tab + 32 * kd + 8 * fq), cb = *(const LAS f32x4*)(tab + 32 * kd + 8 * fq + 4);
.LBB0_498:
	v_add3_u32 v178, 0, v226, v195
	v_add_u32_e32 v179, v178, v185
	ds_read_b64 v[226:227], v179
	v_add_u32_e32 v179, v178, v183
	ds_read_b64 v[228:229], v179
	v_add_u32_e32 v179, v178, v187
	ds_read_b64 v[234:235], v179
	v_add_u32_e32 v179, v178, v213
	ds_read_b64 v[236:237], v179
	s_waitcnt lgkmcnt(0)
	v_mfma_f32_16x16x32_bf16 v[230:233], v[116:119], v[226:229], 0
	v_add_u32_e32 v179, v178, v212
	ds_read_b64 v[246:247], v179
	v_add_u32_e32 v179, v178, v211
	v_mfma_f32_16x16x32_bf16 v[226:229], v[124:127], v[226:229], 0
	ds_read_b64 v[248:249], v179
	v_add_u32_e32 v179, v178, v191
	v_add_u32_e32 v178, v178, v210
	v_mfma_f32_16x16x32_bf16 v[230:233], v[112:115], v[234:237], v[230:233]
	v_sub_f32_e32 v172, v217, v172
	v_mfma_f32_16x16x32_bf16 v[226:229], v[120:123], v[234:237], v[226:229]
	ds_read_b64 v[234:235], v179
	v_add_u32_e32 v179, v225, v215
	v_exp_f32_e32 v172, v172
	s_waitcnt lgkmcnt(0)
	v_mfma_f32_16x16x32_bf16 v[230:233], v[108:111], v[246:249], v[230:233]
	v_sub_f32_e32 v173, v217, v173
	v_exp_f32_e32 v173, v173
	v_sub_f32_e32 v174, v217, v174
	v_mfma_f32_16x16x32_bf16 v[226:229], v[128:131], v[246:249], v[226:229]
	ds_read_b128 v[246:249], v179
	ds_read_b64 v[236:237], v178
	v_exp_f32_e32 v174, v174
	v_sub_f32_e32 v164, v217, v164
	v_exp_f32_e32 v164, v164
	s_waitcnt lgkmcnt(0)
	v_lshlrev_b32_e32 v178, 16, v246
	v_and_b32_e32 v179, 0xffff0000, v246
	v_lshlrev_b32_e32 v225, 16, v247
	v_and_b32_e32 v240, 0xffff0000, v247
	v_cmp_le_i32_e32 vcc, v180, v216
	v_cmp_eq_u32_e64 s[100:101], v180, v216
	s_xnor_b64 vcc, vcc, s[38:39]
	s_or_b64 vcc, vcc, s[100:101]
	v_mfma_f32_16x16x32_bf16 v[230:233], v[104:107], v[234:237], v[230:233]
	v_cndmask_b32_e32 v172, 0, v172, vcc
	v_mul_f32_e32 v172, v172, v178
	v_cmp_eq_u32_e32 vcc, v180, v216
	v_mul_f32_e32 v178, v168, v172
	s_and_b64 vcc, s[38:39], vcc
	v_fma_f32 v168, v168, v172, v203
	v_cndmask_b32_e32 v168, v178, v168, vcc
	v_cmp_lt_i32_e32 vcc, v180, v216
	v_cmp_eq_u32_e64 s[100:101], v218, v216
	s_xnor_b64 vcc, vcc, s[38:39]
	s_or_b64 vcc, vcc, s[100:101]
	v_mfma_f32_16x16x32_bf16 v[226:229], v[132:135], v[234:237], v[226:229]
	v_lshlrev_b32_e32 v234, 16, v248
	v_cndmask_b32_e32 v172, 0, v173, vcc
	v_mul_f32_e32 v172, v172, v179
	v_cmp_eq_u32_e32 vcc, v218, v216
	v_mul_f32_e32 v173, v169, v172
	s_and_b64 vcc, s[38:39], vcc
	v_fma_f32 v169, v169, v172, v203
	v_cndmask_b32_e32 v169, v173, v169, vcc
	v_cmp_le_i32_e32 vcc, v219, v216
	v_cmp_eq_u32_e64 s[100:101], v219, v216
	s_xnor_b64 vcc, vcc, s[38:39]
	s_or_b64 vcc, vcc, s[100:101]
	v_sub_f32_e32 v165, v217, v165
	v_exp_f32_e32 v165, v165
	v_cndmask_b32_e32 v172, 0, v174, vcc
	v_mul_f32_e32 v172, v172, v225
	v_cmp_eq_u32_e32 vcc, v219, v216
	v_mul_f32_e32 v173, v170, v172
	s_and_b64 vcc, s[38:39], vcc
	v_fma_f32 v170, v170, v172, v203
	v_cndmask_b32_e32 v170, v173, v170, vcc
	v_sub_f32_e32 v174, v217, v175
	v_exp_f32_e32 v174, v174
	v_cmp_le_i32_e32 vcc, v220, v216
	v_cmp_eq_u32_e64 s[100:101], v220, v216
	s_xnor_b64 vcc, vcc, s[38:39]
	s_or_b64 vcc, vcc, s[100:101]
	v_and_b32_e32 v235, 0xffff0000, v248
	v_cndmask_b32_e32 v172, 0, v174, vcc
	v_mul_f32_e32 v172, v172, v240
	v_cmp_eq_u32_e32 vcc, v220, v216
	v_mul_f32_e32 v173, v171, v172
	s_and_b64 vcc, s[38:39], vcc
	v_fma_f32 v171, v171, v172, v203
	v_cndmask_b32_e32 v171, v173, v171, vcc
	v_cmp_le_i32_e32 vcc, v221, v216
	v_cmp_eq_u32_e64 s[100:101], v221, v216
	s_xnor_b64 vcc, vcc, s[38:39]
	s_or_b64 vcc, vcc, s[100:101]
	v_sub_f32_e32 v166, v217, v166
	v_exp_f32_e32 v166, v166
	v_cndmask_b32_e32 v164, 0, v164, vcc
	v_mul_f32_e32 v164, v164, v234
	v_cmp_eq_u32_e32 vcc, v221, v216
	v_mul_f32_e32 v172, v160, v164
	s_and_b64 vcc, s[38:39], vcc
	v_fma_f32 v160, v160, v164, v203
	v_cndmask_b32_e32 v164, v172, v160, vcc
	v_cmp_le_i32_e32 vcc, v222, v216
	v_cmp_eq_u32_e64 s[100:101], v222, v216
	s_xnor_b64 vcc, vcc, s[38:39]
	s_or_b64 vcc, vcc, s[100:101]
	v_lshlrev_b32_e32 v236, 16, v249
	v_and_b32_e32 v237, 0xffff0000, v249
	v_cndmask_b32_e32 v160, 0, v165, vcc
	v_mul_f32_e32 v160, v160, v235
	v_cmp_eq_u32_e32 vcc, v222, v216
	v_mul_f32_e32 v165, v161, v160
	s_and_b64 vcc, s[38:39], vcc
	v_fma_f32 v160, v161, v160, v203
	v_cndmask_b32_e32 v165, v165, v160, vcc
	v_cmp_le_i32_e32 vcc, v223, v216
	v_cmp_eq_u32_e64 s[100:101], v223, v216
	s_xnor_b64 vcc, vcc, s[38:39]
	s_or_b64 vcc, vcc, s[100:101]
	ds_read_b32 v174, v214 offset:128
	s_mov_b32 s94, s92
	v_cndmask_b32_e32 v160, 0, v166, vcc
	v_mul_f32_e32 v160, v160, v236
	v_cmp_eq_u32_e32 vcc, v223, v216
	v_mul_f32_e32 v161, v162, v160
	s_and_b64 vcc, s[38:39], vcc
	v_fma_f32 v160, v162, v160, v203
	v_cndmask_b32_e32 v166, v161, v160, vcc
	v_sub_f32_e32 v162, v217, v167
	v_exp_f32_e32 v162, v162
	v_cmp_le_i32_e32 vcc, v224, v216
	v_cmp_eq_u32_e64 s[100:101], v224, v216
	s_xnor_b64 vcc, vcc, s[38:39]
	s_or_b64 vcc, vcc, s[100:101]
	s_mov_b32 s95, s92
	v_or_b32_e32 v173, 32, v176
	v_cndmask_b32_e32 v160, 0, v162, vcc
	v_mul_f32_e32 v160, v160, v237
	v_cmp_eq_u32_e32 vcc, v224, v216
	v_mul_f32_e32 v161, v163, v160
	s_and_b64 vcc, s[38:39], vcc
	v_fma_f32 v160, v163, v160, v203
	v_cndmask_b32_e32 v163, v161, v160, vcc
	v_cvt_pk_bf16_f32 v160, v168, v169
	v_cvt_pk_bf16_f32 v161, v170, v171
	v_cvt_pk_bf16_f32 v162, v164, v165
	v_cvt_pk_bf16_f32 v163, v166, v163
	s_mov_b32 s93, s92
	s_andn2_b64 vcc, exec, s[38:39]
	v_mfma_f32_16x16x32_bf16 v[140:143], v[140:143], v[160:163], v[152:155]
	s_nop 2
	v_exp_f32_e32 v152, v217
	v_mfma_f32_16x16x32_bf16 v[144:147], v[144:147], v[160:163], v[156:159]
	v_add_u32_e32 v154, s5, v216
	v_ashrrev_i32_e32 v155, 31, v154
	v_lshlrev_b64 v[154:155], 13, v[154:155]
	v_pk_fma_f32 v[142:143], v[152:153], v[232:233], v[142:143] op_sel_hi:[0,1,1]
	v_pk_fma_f32 v[140:141], v[152:153], v[230:231], v[140:141] op_sel_hi:[0,1,1]
	v_lshl_add_u64 v[154:155], v[198:199], 0, v[154:155]
	v_cvt_pk_bf16_f32 v140, v140, v141
	v_cvt_pk_bf16_f32 v141, v142, v143
	global_store_dwordx2 v[154:155], v[140:141], off
	v_pk_fma_f32 v[140:141], v[152:153], v[228:229], v[146:147] op_sel_hi:[0,1,1]
	v_pk_fma_f32 v[142:143], v[152:153], v[226:227], v[144:145] op_sel_hi:[0,1,1]
	v_cvt_pk_bf16_f32 v142, v142, v143
	v_cvt_pk_bf16_f32 v143, v140, v141
	global_store_dwordx2 v[154:155], v[142:143], off offset:32
	global_load_dwordx4 v[140:143], v[200:201], off offset:128
	v_cndmask_b32_e64 v152, 0, 1, s[38:39]
	v_mov_b64_e32 v[146:147], s[94:95]
	v_lshlrev_b32_e32 v156, 8, v173
	v_cmp_ne_u32_e64 s[46:47], 1, v152
	v_mov_b64_e32 v[154:155], s[94:95]
	v_mov_b64_e32 v[144:145], s[92:93]
	v_add_u32_e32 v160, s87, v156
	v_mov_b64_e32 v[152:153], s[92:93]
	s_cbranch_vccz .LBB0_528
	s_and_b64 vcc, exec, s[44:45]
	s_cbranch_vccz .LBB0_529

; template <int MODE> __device__ __forceinline__ void ssd_scan_phase(Frame& F, int j, bool ctx_out) {
;     ...
;                 for (int lt = 0; lt < 8; ++lt) {
;                     const int l = 16 * lt + fr; const float cl = tab[l];
;                     f32x4 accd[2], acco[2];
;                     accd[0] = accd[1] = acco[0] = acco[1] = (f32x4){0.f, 0.f, 0.f, 0.f};
;                     const int kd = lt >> 1;
;                     if ((lt & 1) == 0) { xb_cur = xb_nxt; if (kd + 1 < 4) xb_nxt = *(const bf16x8*)(xl + (size_t)16 * T + 32 * (kd + 1)); }
;                     const bf16x8 xa = xf[0][kd], xb = xb_cur;
; #pragma unroll
;                     for (int ks = 0; ks < 4; ++ks) {
;                         const bool full = dir == 0 ? (ks < kd) : (ks > kd);
;                         if (full) {
;                             const bf16x8 gf = *(const LAS bf16x8*)(GS + l * 256 + (((4 * ks + fq) ^ fr) << 4));
;                             const float f1 = __builtin_amdgcn_exp2f(cl - tab[dir == 0 ? 32 * ks + 31 : 32 * ks]);
;                             const f32x4 z4 = (f32x4){0.f, 0.f, 0.f, 0.f};
;                             const f32x4 t0 = __builtin_amdgcn_mfma_f32_16x16x32_bf16(xs2[0][ks], gf, z4, 0, 0, 0), t1 = __builtin_amdgcn_mfma_f32_16x16x32_bf16(xs2[1][ks], gf, z4, 0, 0, 0);
;                             accd[0] += t0 * f1; accd[1] += t1 * f1;
;                         }
;                     }
; #pragma unroll
;                     for (int q = 0; q < 4; ++q) {
;                         const u32x2 lo = *(const LAS u32x2*)(CS + l * 256 + (((4 * q + (fq >> 1)) ^ fr) << 4) + (fq & 1) * 8), hi = *(const LAS u32x2*)(CS + l * 256 + (((4 * q + 2 + (fq >> 1)) ^ fr) << 4) + (fq & 1) * 8);
;                         u32x4 c4; c4.x = lo.x; c4.y = lo.y; c4.z = hi.x; c4.w = hi.y; const bf16x8 cfr = __builtin_bit_cast(bf16x8, c4);
;                         acco[0] = __builtin_amdgcn_mfma_f32_16x16x32_bf16(hf[0][q], cfr, acco[0], 0, 0, 0);
;                         acco[1] = __builtin_amdgcn_mfma_f32_16x16x32_bf16(hf[1][q], cfr, acco[1], 0, 0, 0);
;                     }
;                     {
;                         float gg[8]; unpack8(*(const LAS u32x4*)(GS + l * 256 + (((4 * kd + fq) ^ fr) << 4)), gg);
;                         const f32x4 ca = *(const LAS f32x4*)(tab + 32 * kd + 8 * fq), cb = *(const LAS f32x4*)(tab + 32 * kd + 8 * fq + 4);
.LBB0_502:
	v_add3_u32 v161, 0, v156, v195
	v_add_u32_e32 v156, v161, v185
	v_add_u32_e32 v157, v161, v183
	ds_read_b64 v[162:163], v156
	ds_read_b64 v[164:165], v157
	v_add_u32_e32 v156, v161, v187
	v_add_u32_e32 v158, v161, v213
	ds_read_b64 v[156:157], v156
	ds_read_b32 v175, v214 offset:192
	ds_read_b64 v[158:159], v158
	s_waitcnt lgkmcnt(0)
	v_mfma_f32_16x16x32_bf16 v[166:169], v[116:119], v[162:165], 0
	v_add_u32_e32 v170, v161, v212
	v_add_u32_e32 v171, v161, v211
	v_add_u32_e32 v172, v161, v191
	v_mfma_f32_16x16x32_bf16 v[162:165], v[124:127], v[162:165], 0
	ds_read_b64 v[216:217], v170
	ds_read_b64 v[218:219], v171
	ds_read_b64 v[220:221], v172
	v_add_u32_e32 v161, v161, v210
	v_lshlrev_b32_e32 v172, 4, v207
	v_mfma_f32_16x16x32_bf16 v[166:169], v[112:115], v[156:159], v[166:169]
	ds_read_b64 v[222:223], v161
	v_add_u32_e32 v160, v160, v172
	s_mov_b32 s94, s92
	v_mfma_f32_16x16x32_bf16 v[156:159], v[120:123], v[156:159], v[162:165]
	s_mov_b32 s95, s92
	s_mov_b32 s93, s92
	s_waitcnt lgkmcnt(0)
	v_mfma_f32_16x16x32_bf16 v[162:165], v[108:111], v[216:219], v[166:169]
	s_nop 2
	ds_read_b128 v[168:171], v197 offset:128
	v_mfma_f32_16x16x32_bf16 v[156:159], v[128:131], v[216:219], v[156:159]
	ds_read_b128 v[216:219], v160
	s_waitcnt lgkmcnt(0)
	v_sub_f32_e32 v234, v174, v170
	v_mfma_f32_16x16x32_bf16 v[228:231], v[132:135], v[220:223], v[156:159]
	v_lshlrev_b32_e32 v178, 16, v216
	v_and_b32_e32 v179, 0xffff0000, v216
	v_lshlrev_b32_e32 v232, 16, v219
	s_nop 0
	v_sub_f32_e32 v156, v174, v168
	v_exp_f32_e32 v216, v156
	v_mfma_f32_16x16x32_bf16 v[224:227], v[104:107], v[220:223], v[162:165]
	v_lshlrev_b32_e32 v220, 16, v217
	v_and_b32_e32 v221, 0xffff0000, v217
	v_cndmask_b32_e64 v216, 0, v216, s[40:41]
	ds_read_b128 v[160:163], v197 offset:144
	ds_read_b128 v[164:167], v197 offset:640
	v_mul_f32_e32 v178, v216, v178
	v_and_b32_e32 v233, 0xffff0000, v219
	v_sub_f32_e32 v219, v174, v169
	v_lshlrev_b32_e32 v222, 16, v218
	s_waitcnt lgkmcnt(0)
	v_mul_f32_e32 v216, v164, v178
	v_fma_f32 v178, v164, v178, v203
	v_cndmask_b32_e64 v178, v216, v178, s[42:43]
	v_add_u32_e32 v216, 33, v180
	v_and_b32_e32 v223, 0xffff0000, v218
	v_exp_f32_e32 v219, v219
	v_exp_f32_e32 v234, v234
	v_sub_f32_e32 v235, v174, v171
	v_cmp_le_i32_e32 vcc, v216, v173
	v_cmp_eq_u32_e64 s[100:101], v216, v173
	s_xnor_b64 vcc, vcc, s[38:39]
	s_or_b64 vcc, vcc, s[100:101]
	v_exp_f32_e32 v235, v235
	v_sub_f32_e32 v236, v174, v160
	v_cndmask_b32_e32 v217, 0, v219, vcc
	v_mul_f32_e32 v179, v217, v179
	v_cmp_eq_u32_e32 vcc, v216, v173
	v_mul_f32_e32 v217, v165, v179
	v_fma_f32 v179, v165, v179, v203
	s_and_b64 vcc, s[38:39], vcc
	v_cndmask_b32_e32 v179, v217, v179, vcc
	v_add_u32_e32 v217, 34, v180
	v_exp_f32_e32 v236, v236
	ds_read_b128 v[156:159], v197 offset:656
	v_sub_f32_e32 v237, v174, v161
	v_exp_f32_e32 v237, v237
	v_cmp_le_i32_e32 vcc, v217, v173
	v_cmp_eq_u32_e64 s[100:101], v217, v173
	s_xnor_b64 vcc, vcc, s[38:39]
	s_or_b64 vcc, vcc, s[100:101]
	v_sub_f32_e32 v240, v174, v162
	v_exp_f32_e32 v240, v240
	v_cndmask_b32_e32 v218, 0, v234, vcc
	v_mul_f32_e32 v218, v218, v220
	v_cmp_eq_u32_e32 vcc, v217, v173
	v_mul_f32_e32 v219, v166, v218
	v_fma_f32 v218, v166, v218, v203
	s_and_b64 vcc, s[38:39], vcc
	v_cndmask_b32_e32 v234, v219, v218, vcc
	v_add_u32_e32 v218, 35, v180
	v_sub_f32_e32 v246, v174, v163
	v_exp_f32_e32 v246, v246
	v_exp_f32_e32 v174, v174
	s_nop 0
	v_cmp_le_i32_e32 vcc, v218, v173
	v_cmp_eq_u32_e64 s[100:101], v218, v173
	s_xnor_b64 vcc, vcc, s[38:39]
	s_or_b64 vcc, vcc, s[100:101]
	v_cndmask_b32_e32 v219, 0, v235, vcc
	v_mul_f32_e32 v219, v219, v221
	v_cmp_eq_u32_e32 vcc, v218, v173
	v_mul_f32_e32 v220, v167, v219
	v_fma_f32 v219, v167, v219, v203
	s_and_b64 vcc, s[38:39], vcc
	v_cndmask_b32_e32 v235, v220, v219, vcc
	v_add_u32_e32 v219, 36, v180
	s_nop 1
	s_nop 1
	v_cmp_le_i32_e32 vcc, v219, v173
	v_cmp_eq_u32_e64 s[100:101], v219, v173
	s_xnor_b64 vcc, vcc, s[38:39]
	s_or_b64 vcc, vcc, s[100:101]
	v_cndmask_b32_e32 v220, 0, v236, vcc
	v_mul_f32_e32 v220, v220, v222
	v_cmp_eq_u32_e32 vcc, v219, v173
	s_waitcnt lgkmcnt(0)
	v_mul_f32_e32 v221, v156, v220
	v_fma_f32 v220, v156, v220, v203
	s_and_b64 vcc, s[38:39], vcc
	v_cndmask_b32_e32 v236, v221, v220, vcc
	v_add_u32_e32 v220, 37, v180
	s_nop 1
	s_nop 1
	v_cmp_le_i32_e32 vcc, v220, v173
	v_cmp_eq_u32_e64 s[100:101], v220, v173
	s_xnor_b64 vcc, vcc, s[38:39]
	s_or_b64 vcc, vcc, s[100:101]
	v_cndmask_b32_e32 v221, 0, v237, vcc
	v_mul_f32_e32 v221, v221, v223
	v_cmp_eq_u32_e32 vcc, v220, v173
	v_mul_f32_e32 v222, v157, v221
	v_fma_f32 v221, v157, v221, v203
	s_and_b64 vcc, s[38:39], vcc
	v_cndmask_b32_e32 v223, v222, v221, vcc
	v_add_u32_e32 v221, 38, v180
	s_nop 1
	s_nop 1
	v_cmp_le_i32_e32 vcc, v221, v173
	v_cmp_eq_u32_e64 s[100:101], v221, v173
	s_xnor_b64 vcc, vcc, s[38:39]
	s_or_b64 vcc, vcc, s[100:101]
	v_cndmask_b32_e32 v222, 0, v240, vcc
	v_mul_f32_e32 v222, v222, v232
	v_cmp_eq_u32_e32 vcc, v221, v173
	v_mul_f32_e32 v232, v158, v222
	v_fma_f32 v222, v158, v222, v203
	s_and_b64 vcc, s[38:39], vcc
	v_cndmask_b32_e32 v237, v232, v222, vcc
	v_add_u32_e32 v222, 39, v180
	s_nop 1
	s_nop 1
	v_cmp_le_i32_e32 vcc, v222, v173
	v_cmp_eq_u32_e64 s[100:101], v222, v173
	s_xnor_b64 vcc, vcc, s[38:39]
	s_or_b64 vcc, vcc, s[100:101]
	v_cndmask_b32_e32 v232, 0, v246, vcc
	v_mul_f32_e32 v232, v232, v233
	v_cmp_eq_u32_e32 vcc, v222, v173
	v_mul_f32_e32 v233, v159, v232
	v_fma_f32 v232, v159, v232, v203
	s_and_b64 vcc, s[38:39], vcc
	v_cndmask_b32_e32 v240, v233, v232, vcc
	v_cvt_pk_bf16_f32 v232, v178, v179
	v_cvt_pk_bf16_f32 v233, v234, v235
	v_cvt_pk_bf16_f32 v234, v236, v223
	v_cvt_pk_bf16_f32 v235, v237, v240
	s_and_b64 vcc, exec, s[46:47]
	s_waitcnt vmcnt(5)
	v_mfma_f32_16x16x32_bf16 v[144:147], v[148:151], v[232:235], v[144:147]
	v_mfma_f32_16x16x32_bf16 v[246:249], v[136:139], v[232:235], v[152:155]
	v_add_u32_e32 v232, s5, v173
	v_ashrrev_i32_e32 v233, 31, v232
	v_lshlrev_b64 v[232:233], 13, v[232:233]
	s_nop 3
	v_pk_fma_f32 v[146:147], v[174:175], v[230:231], v[146:147] op_sel_hi:[0,1,1]
	v_pk_fma_f32 v[144:145], v[174:175], v[228:229], v[144:145] op_sel_hi:[0,1,1]
	v_lshl_add_u64 v[232:233], v[198:199], 0, v[232:233]
	v_cvt_pk_bf16_f32 v144, v144, v145
	v_cvt_pk_bf16_f32 v145, v146, v147
	v_or_b32_e32 v173, 48, v176
	v_mov_b64_e32 v[154:155], s[94:95]
	v_pk_fma_f32 v[226:227], v[174:175], v[226:227], v[248:249] op_sel_hi:[0,1,1]
	v_pk_fma_f32 v[224:225], v[174:175], v[224:225], v[246:247] op_sel_hi:[0,1,1]
	global_store_dwordx2 v[232:233], v[144:145], off offset:32
	v_lshlrev_b32_e32 v223, 8, v173
	v_mov_b64_e32 v[146:147], s[94:95]
	v_mov_b64_e32 v[152:153], s[92:93]
	v_cvt_pk_bf16_f32 v224, v224, v225
	v_cvt_pk_bf16_f32 v225, v226, v227
	v_add_u32_e32 v174, s87, v223
	v_mov_b64_e32 v[144:145], s[92:93]
	global_store_dwordx2 v[232:233], v[224:225], off
	s_cbranch_vccz .LBB0_530
	s_and_b64 vcc, exec, s[44:45]
	s_cbranch_vccz .LBB0_531

; template <int MODE> __device__ __forceinline__ void ssd_scan_phase(Frame& F, int j, bool ctx_out) {
;     ...
;                 for (int lt = 0; lt < 8; ++lt) {
;                     const int l = 16 * lt + fr; const float cl = tab[l];
;                     f32x4 accd[2], acco[2];
;                     accd[0] = accd[1] = acco[0] = acco[1] = (f32x4){0.f, 0.f, 0.f, 0.f};
;                     const int kd = lt >> 1;
;                     if ((lt & 1) == 0) { xb_cur = xb_nxt; if (kd + 1 < 4) xb_nxt = *(const bf16x8*)(xl + (size_t)16 * T + 32 * (kd + 1)); }
;                     const bf16x8 xa = xf[0][kd], xb = xb_cur;
; #pragma unroll
;                     for (int ks = 0; ks < 4; ++ks) {
;                         const bool full = dir == 0 ? (ks < kd) : (ks > kd);
;                         if (full) {
;                             const bf16x8 gf = *(const LAS bf16x8*)(GS + l * 256 + (((4 * ks + fq) ^ fr) << 4));
;                             const float f1 = __builtin_amdgcn_exp2f(cl - tab[dir == 0 ? 32 * ks + 31 : 32 * ks]);
;                             const f32x4 z4 = (f32x4){0.f, 0.f, 0.f, 0.f};
;                             const f32x4 t0 = __builtin_amdgcn_mfma_f32_16x16x32_bf16(xs2[0][ks], gf, z4, 0, 0, 0), t1 = __builtin_amdgcn_mfma_f32_16x16x32_bf16(xs2[1][ks], gf, z4, 0, 0, 0);
;                             accd[0] += t0 * f1; accd[1] += t1 * f1;
;                         }
;                     }
; #pragma unroll
;                     for (int q = 0; q < 4; ++q) {
;                         const u32x2 lo = *(const LAS u32x2*)(CS + l * 256 + (((4 * q + (fq >> 1)) ^ fr) << 4) + (fq & 1) * 8), hi = *(const LAS u32x2*)(CS + l * 256 + (((4 * q + 2 + (fq >> 1)) ^ fr) << 4) + (fq & 1) * 8);
;                         u32x4 c4; c4.x = lo.x; c4.y = lo.y; c4.z = hi.x; c4.w = hi.y; const bf16x8 cfr = __builtin_bit_cast(bf16x8, c4);
;                         acco[0] = __builtin_amdgcn_mfma_f32_16x16x32_bf16(hf[0][q], cfr, acco[0], 0, 0, 0);
;                         acco[1] = __builtin_amdgcn_mfma_f32_16x16x32_bf16(hf[1][q], cfr, acco[1], 0, 0, 0);
;                     }
;                     {
;                         float gg[8]; unpack8(*(const LAS u32x4*)(GS + l * 256 + (((4 * kd + fq) ^ fr) << 4)), gg);
;                         const f32x4 ca = *(const LAS f32x4*)(tab + 32 * kd + 8 * fq), cb = *(const LAS f32x4*)(tab + 32 * kd + 8 * fq + 4);
.LBB0_506:
	v_add3_u32 v178, 0, v223, v195
	v_add_u32_e32 v179, v178, v185
	ds_read_b64 v[224:225], v179
	v_add_u32_e32 v179, v178, v183
	ds_read_b64 v[226:227], v179
	v_add_u32_e32 v179, v178, v187
	ds_read_b64 v[232:233], v179
	v_add_u32_e32 v179, v178, v213
	ds_read_b64 v[234:235], v179
	s_waitcnt lgkmcnt(2)
	v_mfma_f32_16x16x32_bf16 v[228:231], v[116:119], v[224:227], 0
	v_add_u32_e32 v179, v178, v212
	ds_read_b64 v[246:247], v179
	v_add_u32_e32 v179, v178, v211
	v_mfma_f32_16x16x32_bf16 v[224:227], v[124:127], v[224:227], 0
	ds_read_b64 v[248:249], v179
	v_add_u32_e32 v174, v174, v172
	v_sub_f32_e32 v168, v175, v168
	s_waitcnt lgkmcnt(2)
	v_mfma_f32_16x16x32_bf16 v[228:231], v[112:115], v[232:235], v[228:231]
	v_exp_f32_e32 v168, v168
	v_add_u32_e32 v179, v178, v191
	v_add_u32_e32 v178, v178, v210
	v_mfma_f32_16x16x32_bf16 v[224:227], v[120:123], v[232:235], v[224:227]
	ds_read_b64 v[232:233], v179
	ds_read_b64 v[234:235], v178
	v_sub_f32_e32 v169, v175, v169
	s_waitcnt lgkmcnt(2)
	v_mfma_f32_16x16x32_bf16 v[228:231], v[108:111], v[246:249], v[228:231]
	v_exp_f32_e32 v169, v169
	v_sub_f32_e32 v170, v175, v170
	v_exp_f32_e32 v170, v170
	v_mfma_f32_16x16x32_bf16 v[224:227], v[128:131], v[246:249], v[224:227]
	ds_read_b128 v[246:249], v174
	v_add_u32_e32 v174, 32, v180
	s_waitcnt lgkmcnt(1)
	v_mfma_f32_16x16x32_bf16 v[228:231], v[104:107], v[232:235], v[228:231]
	v_cmp_le_i32_e32 vcc, v174, v173
	v_cmp_eq_u32_e64 s[100:101], v174, v173
	s_xnor_b64 vcc, vcc, s[38:39]
	s_or_b64 vcc, vcc, s[100:101]
	s_waitcnt lgkmcnt(0)
	v_lshlrev_b32_e32 v178, 16, v246
	v_cndmask_b32_e32 v168, 0, v168, vcc
	v_mul_f32_e32 v168, v168, v178
	v_cmp_eq_u32_e32 vcc, v174, v173
	v_mul_f32_e32 v178, v164, v168
	s_and_b64 vcc, s[38:39], vcc
	v_fma_f32 v164, v164, v168, v203
	v_cndmask_b32_e32 v164, v178, v164, vcc
	v_and_b32_e32 v179, 0xffff0000, v246
	v_cmp_le_i32_e32 vcc, v216, v173
	v_cmp_eq_u32_e64 s[100:101], v216, v173
	s_xnor_b64 vcc, vcc, s[38:39]
	s_or_b64 vcc, vcc, s[100:101]
	v_lshlrev_b32_e32 v223, 16, v247
	v_cndmask_b32_e32 v168, 0, v169, vcc
	v_mul_f32_e32 v168, v168, v179
	v_cmp_eq_u32_e32 vcc, v216, v173
	v_mul_f32_e32 v169, v165, v168
	s_and_b64 vcc, s[38:39], vcc
	v_fma_f32 v165, v165, v168, v203
	v_cndmask_b32_e32 v165, v169, v165, vcc
	v_cmp_le_i32_e32 vcc, v217, v173
	v_cmp_eq_u32_e64 s[100:101], v217, v173
	s_xnor_b64 vcc, vcc, s[38:39]
	s_or_b64 vcc, vcc, s[100:101]
	v_mfma_f32_16x16x32_bf16 v[224:227], v[132:135], v[232:235], v[224:227]
	v_and_b32_e32 v232, 0xffff0000, v247
	v_cndmask_b32_e32 v168, 0, v170, vcc
	v_mul_f32_e32 v168, v168, v223
	v_cmp_eq_u32_e32 vcc, v217, v173
	v_mul_f32_e32 v169, v166, v168
	s_and_b64 vcc, s[38:39], vcc
	v_fma_f32 v166, v166, v168, v203
	v_cndmask_b32_e32 v166, v169, v166, vcc
	v_sub_f32_e32 v170, v175, v171
	v_exp_f32_e32 v170, v170
	v_cmp_le_i32_e32 vcc, v218, v173
	v_cmp_eq_u32_e64 s[100:101], v218, v173
	s_xnor_b64 vcc, vcc, s[38:39]
	s_or_b64 vcc, vcc, s[100:101]
	v_sub_f32_e32 v160, v175, v160
	v_cndmask_b32_e32 v168, 0, v170, vcc
	v_mul_f32_e32 v168, v168, v232
	v_cmp_eq_u32_e32 vcc, v218, v173
	v_mul_f32_e32 v169, v167, v168
	s_and_b64 vcc, s[38:39], vcc
	v_fma_f32 v167, v167, v168, v203
	v_cndmask_b32_e32 v167, v169, v167, vcc
	v_exp_f32_e32 v160, v160
	v_cmp_le_i32_e32 vcc, v219, v173
	v_cmp_eq_u32_e64 s[100:101], v219, v173
	s_xnor_b64 vcc, vcc, s[38:39]
	s_or_b64 vcc, vcc, s[100:101]
	v_lshlrev_b32_e32 v233, 16, v248
	v_cndmask_b32_e32 v160, 0, v160, vcc
	v_mul_f32_e32 v160, v160, v233
	v_cmp_eq_u32_e32 vcc, v219, v173
	v_mul_f32_e32 v168, v156, v160
	s_and_b64 vcc, s[38:39], vcc
	v_fma_f32 v156, v156, v160, v203
	v_cndmask_b32_e32 v160, v168, v156, vcc
	v_sub_f32_e32 v161, v175, v161
	v_exp_f32_e32 v161, v161
	v_cmp_le_i32_e32 vcc, v220, v173
	v_cmp_eq_u32_e64 s[100:101], v220, v173
	s_xnor_b64 vcc, vcc, s[38:39]
	s_or_b64 vcc, vcc, s[100:101]
	v_and_b32_e32 v234, 0xffff0000, v248
	v_cndmask_b32_e32 v156, 0, v161, vcc
	v_mul_f32_e32 v156, v156, v234
	v_cmp_eq_u32_e32 vcc, v220, v173
	v_mul_f32_e32 v161, v157, v156
	s_and_b64 vcc, s[38:39], vcc
	v_fma_f32 v156, v157, v156, v203
	v_cndmask_b32_e32 v161, v161, v156, vcc
	v_sub_f32_e32 v162, v175, v162
	v_exp_f32_e32 v162, v162
	v_cmp_le_i32_e32 vcc, v221, v173
	v_cmp_eq_u32_e64 s[100:101], v221, v173
	s_xnor_b64 vcc, vcc, s[38:39]
	s_or_b64 vcc, vcc, s[100:101]
	v_lshlrev_b32_e32 v235, 16, v249
	v_cndmask_b32_e32 v156, 0, v162, vcc
	v_mul_f32_e32 v156, v156, v235
	v_cmp_eq_u32_e32 vcc, v221, v173
	v_mul_f32_e32 v157, v158, v156
	s_and_b64 vcc, s[38:39], vcc
	v_fma_f32 v156, v158, v156, v203
	v_cndmask_b32_e32 v162, v157, v156, vcc
	v_sub_f32_e32 v158, v175, v163
	v_exp_f32_e32 v158, v158
	v_cmp_le_i32_e32 vcc, v222, v173
	v_cmp_eq_u32_e64 s[100:101], v222, v173
	s_xnor_b64 vcc, vcc, s[38:39]
	s_or_b64 vcc, vcc, s[100:101]
	v_and_b32_e32 v236, 0xffff0000, v249
	ds_read_b32 v170, v214 offset:256
	v_cndmask_b32_e32 v156, 0, v158, vcc
	v_mul_f32_e32 v156, v156, v236
	v_cmp_eq_u32_e32 vcc, v222, v173
	v_mul_f32_e32 v157, v159, v156
	s_and_b64 vcc, s[38:39], vcc
	v_fma_f32 v156, v159, v156, v203
	v_cndmask_b32_e32 v159, v157, v156, vcc
	v_cvt_pk_bf16_f32 v156, v164, v165
	v_cvt_pk_bf16_f32 v157, v166, v167
	v_cvt_pk_bf16_f32 v158, v160, v161
	v_cvt_pk_bf16_f32 v159, v162, v159
	s_mov_b32 s94, s92
	s_mov_b32 s95, s92
	v_mfma_f32_16x16x32_bf16 v[136:139], v[136:139], v[156:159], v[144:147]
	v_or_b32_e32 v169, 64, v176
	s_mov_b32 s93, s92
	s_and_b64 vcc, exec, s[46:47]
	v_mfma_f32_16x16x32_bf16 v[144:147], v[148:151], v[156:159], v[152:155]
	v_exp_f32_e32 v148, v175
	v_add_u32_e32 v150, s5, v173
	v_ashrrev_i32_e32 v151, 31, v150
	v_lshlrev_b64 v[150:151], 13, v[150:151]
	v_pk_fma_f32 v[138:139], v[148:149], v[230:231], v[138:139] op_sel_hi:[0,1,1]
	v_pk_fma_f32 v[136:137], v[148:149], v[228:229], v[136:137] op_sel_hi:[0,1,1]
	v_lshl_add_u64 v[150:151], v[198:199], 0, v[150:151]
	v_cvt_pk_bf16_f32 v136, v136, v137
	v_cvt_pk_bf16_f32 v137, v138, v139
	global_store_dwordx2 v[150:151], v[136:137], off
	v_pk_fma_f32 v[136:137], v[148:149], v[226:227], v[146:147] op_sel_hi:[0,1,1]
	v_pk_fma_f32 v[138:139], v[148:149], v[224:225], v[144:145] op_sel_hi:[0,1,1]
	v_cvt_pk_bf16_f32 v138, v138, v139
	v_cvt_pk_bf16_f32 v139, v136, v137
	global_store_dwordx2 v[150:151], v[138:139], off offset:32
	global_load_dwordx4 v[136:139], v[200:201], off offset:192
	v_mov_b64_e32 v[146:147], s[94:95]
	v_lshlrev_b32_e32 v152, 8, v169
	v_mov_b64_e32 v[150:151], s[94:95]
	v_mov_b64_e32 v[144:145], s[92:93]
	v_add_u32_e32 v156, s87, v152
	v_mov_b64_e32 v[148:149], s[92:93]
	s_cbranch_vccz .LBB0_532
	s_and_b64 vcc, exec, s[46:47]
	s_cbranch_vccz .LBB0_533

; template <int MODE> __device__ __forceinline__ void ssd_scan_phase(Frame& F, int j, bool ctx_out) {
;     ...
;                 for (int lt = 0; lt < 8; ++lt) {
;                     const int l = 16 * lt + fr; const float cl = tab[l];
;                     f32x4 accd[2], acco[2];
;                     accd[0] = accd[1] = acco[0] = acco[1] = (f32x4){0.f, 0.f, 0.f, 0.f};
;                     const int kd = lt >> 1;
;                     if ((lt & 1) == 0) { xb_cur = xb_nxt; if (kd + 1 < 4) xb_nxt = *(const bf16x8*)(xl + (size_t)16 * T + 32 * (kd + 1)); }
;                     const bf16x8 xa = xf[0][kd], xb = xb_cur;
; #pragma unroll
;                     for (int ks = 0; ks < 4; ++ks) {
;                         const bool full = dir == 0 ? (ks < kd) : (ks > kd);
;                         if (full) {
;                             const bf16x8 gf = *(const LAS bf16x8*)(GS + l * 256 + (((4 * ks + fq) ^ fr) << 4));
;                             const float f1 = __builtin_amdgcn_exp2f(cl - tab[dir == 0 ? 32 * ks + 31 : 32 * ks]);
;                             const f32x4 z4 = (f32x4){0.f, 0.f, 0.f, 0.f};
;                             const f32x4 t0 = __builtin_amdgcn_mfma_f32_16x16x32_bf16(xs2[0][ks], gf, z4, 0, 0, 0), t1 = __builtin_amdgcn_mfma_f32_16x16x32_bf16(xs2[1][ks], gf, z4, 0, 0, 0);
;                             accd[0] += t0 * f1; accd[1] += t1 * f1;
;                         }
;                     }
; #pragma unroll
;                     for (int q = 0; q < 4; ++q) {
;                         const u32x2 lo = *(const LAS u32x2*)(CS + l * 256 + (((4 * q + (fq >> 1)) ^ fr) << 4) + (fq & 1) * 8), hi = *(const LAS u32x2*)(CS + l * 256 + (((4 * q + 2 + (fq >> 1)) ^ fr) << 4) + (fq & 1) * 8);
;                         u32x4 c4; c4.x = lo.x; c4.y = lo.y; c4.z = hi.x; c4.w = hi.y; const bf16x8 cfr = __builtin_bit_cast(bf16x8, c4);
;                         acco[0] = __builtin_amdgcn_mfma_f32_16x16x32_bf16(hf[0][q], cfr, acco[0], 0, 0, 0);
;                         acco[1] = __builtin_amdgcn_mfma_f32_16x16x32_bf16(hf[1][q], cfr, acco[1], 0, 0, 0);
;                     }
;                     {
;                         float gg[8]; unpack8(*(const LAS u32x4*)(GS + l * 256 + (((4 * kd + fq) ^ fr) << 4)), gg);
;                         const f32x4 ca = *(const LAS f32x4*)(tab + 32 * kd + 8 * fq), cb = *(const LAS f32x4*)(tab + 32 * kd + 8 * fq + 4);
.LBB0_510:
	v_add3_u32 v157, 0, v152, v195
	v_add_u32_e32 v152, v157, v185
	v_add_u32_e32 v153, v157, v183
	ds_read_b64 v[158:159], v152
	ds_read_b64 v[160:161], v153
	v_add_u32_e32 v152, v157, v187
	v_add_u32_e32 v154, v157, v213
	ds_read_b64 v[152:153], v152
	ds_read_b32 v171, v214 offset:320
	ds_read_b64 v[154:155], v154
	s_waitcnt lgkmcnt(3)
	v_mfma_f32_16x16x32_bf16 v[162:165], v[116:119], v[158:161], 0
	v_add_u32_e32 v166, v157, v212
	v_add_u32_e32 v167, v157, v211
	v_add_u32_e32 v168, v157, v191
	v_mfma_f32_16x16x32_bf16 v[158:161], v[124:127], v[158:161], 0
	ds_read_b64 v[216:217], v166
	ds_read_b64 v[218:219], v167
	ds_read_b64 v[220:221], v168
	v_add_u32_e32 v157, v157, v210
	ds_read_b64 v[222:223], v157
	s_waitcnt lgkmcnt(4)
	v_mfma_f32_16x16x32_bf16 v[162:165], v[112:115], v[152:155], v[162:165]
	v_lshlrev_b32_e32 v168, 4, v206
	v_add_u32_e32 v156, v156, v168
	s_mov_b32 s94, s92
	v_mfma_f32_16x16x32_bf16 v[152:155], v[120:123], v[152:155], v[158:161]
	s_mov_b32 s95, s92
	s_mov_b32 s93, s92
	s_waitcnt lgkmcnt(2)
	v_mfma_f32_16x16x32_bf16 v[158:161], v[108:111], v[216:219], v[162:165]
	s_nop 2
	ds_read_b128 v[164:167], v197 offset:256
	v_mfma_f32_16x16x32_bf16 v[152:155], v[128:131], v[216:219], v[152:155]
	ds_read_b128 v[216:219], v156
	s_waitcnt lgkmcnt(1)
	v_sub_f32_e32 v228, v170, v165
	v_mfma_f32_16x16x32_bf16 v[224:227], v[104:107], v[220:223], v[158:161]
	s_waitcnt lgkmcnt(0)
	v_lshlrev_b32_e32 v173, 16, v216
	v_and_b32_e32 v174, 0xffff0000, v216
	v_lshlrev_b32_e32 v175, 16, v217
	v_mfma_f32_16x16x32_bf16 v[220:223], v[132:135], v[220:223], v[152:155]
	ds_read_b128 v[156:159], v197 offset:272
	ds_read_b128 v[160:163], v197 offset:768
	v_and_b32_e32 v178, 0xffff0000, v217
	v_sub_f32_e32 v152, v170, v164
	v_exp_f32_e32 v200, v152
	v_lshlrev_b32_e32 v179, 16, v218
	v_and_b32_e32 v216, 0xffff0000, v218
	v_lshlrev_b32_e32 v217, 16, v219
	v_cndmask_b32_e64 v200, 0, v200, s[40:41]
	v_mul_f32_e32 v173, v200, v173
	s_waitcnt lgkmcnt(0)
	v_mul_f32_e32 v200, v160, v173
	v_fma_f32 v173, v160, v173, v203
	v_and_b32_e32 v218, 0xffff0000, v219
	v_cndmask_b32_e64 v219, v200, v173, s[42:43]
	v_add_u32_e32 v173, 0x41, v180
	v_exp_f32_e32 v228, v228
	v_sub_f32_e32 v229, v170, v166
	v_exp_f32_e32 v229, v229
	v_sub_f32_e32 v230, v170, v167
	v_cmp_le_i32_e32 vcc, v173, v169
	v_cmp_eq_u32_e64 s[100:101], v173, v169
	s_xnor_b64 vcc, vcc, s[38:39]
	s_or_b64 vcc, vcc, s[100:101]
	v_exp_f32_e32 v230, v230
	v_sub_f32_e32 v231, v170, v156
	v_cndmask_b32_e32 v200, 0, v228, vcc
	v_mul_f32_e32 v174, v200, v174
	v_cmp_eq_u32_e32 vcc, v173, v169
	v_mul_f32_e32 v200, v161, v174
	v_fma_f32 v174, v161, v174, v203
	s_and_b64 vcc, s[38:39], vcc
	v_cndmask_b32_e32 v228, v200, v174, vcc
	v_add_u32_e32 v174, 0x42, v180
	v_exp_f32_e32 v231, v231
	ds_read_b128 v[152:155], v197 offset:784
	v_sub_f32_e32 v232, v170, v157
	v_exp_f32_e32 v232, v232
	v_cmp_le_i32_e32 vcc, v174, v169
	v_cmp_eq_u32_e64 s[100:101], v174, v169
	s_xnor_b64 vcc, vcc, s[38:39]
	s_or_b64 vcc, vcc, s[100:101]
	v_sub_f32_e32 v233, v170, v158
	v_exp_f32_e32 v233, v233
	v_cndmask_b32_e32 v200, 0, v229, vcc
	v_mul_f32_e32 v175, v200, v175
	v_cmp_eq_u32_e32 vcc, v174, v169
	v_mul_f32_e32 v200, v162, v175
	v_fma_f32 v175, v162, v175, v203
	s_and_b64 vcc, s[38:39], vcc
	v_cndmask_b32_e32 v229, v200, v175, vcc
	v_add_u32_e32 v175, 0x43, v180
	v_sub_f32_e32 v234, v170, v159
	v_exp_f32_e32 v234, v234
	v_cvt_pk_bf16_f32 v228, v219, v228
	v_exp_f32_e32 v170, v170
	v_cmp_le_i32_e32 vcc, v175, v169
	v_cmp_eq_u32_e64 s[100:101], v175, v169
	s_xnor_b64 vcc, vcc, s[38:39]
	s_or_b64 vcc, vcc, s[100:101]
	v_cndmask_b32_e32 v200, 0, v230, vcc
	v_mul_f32_e32 v178, v200, v178
	v_cmp_eq_u32_e32 vcc, v175, v169
	v_mul_f32_e32 v200, v163, v178
	v_fma_f32 v178, v163, v178, v203
	s_and_b64 vcc, s[38:39], vcc
	v_cndmask_b32_e32 v178, v200, v178, vcc
	v_add_u32_e32 v200, 0x44, v180
	v_cvt_pk_bf16_f32 v229, v229, v178
	s_nop 0
	s_nop 1
	v_cmp_le_i32_e32 vcc, v200, v169
	v_cmp_eq_u32_e64 s[100:101], v200, v169
	s_xnor_b64 vcc, vcc, s[38:39]
	s_or_b64 vcc, vcc, s[100:101]
	v_cndmask_b32_e32 v201, 0, v231, vcc
	v_mul_f32_e32 v179, v201, v179
	v_cmp_eq_u32_e32 vcc, v200, v169
	s_waitcnt lgkmcnt(0)
	v_mul_f32_e32 v201, v152, v179
	v_fma_f32 v179, v152, v179, v203
	s_and_b64 vcc, s[38:39], vcc
	v_cndmask_b32_e32 v179, v201, v179, vcc
	v_add_u32_e32 v201, 0x45, v180
	s_nop 1
	s_nop 1
	v_cmp_le_i32_e32 vcc, v201, v169
	v_cmp_eq_u32_e64 s[100:101], v201, v169
	s_xnor_b64 vcc, vcc, s[38:39]
	s_or_b64 vcc, vcc, s[100:101]
	v_cndmask_b32_e32 v230, 0, v232, vcc
	v_mul_f32_e32 v216, v230, v216
	v_cmp_eq_u32_e32 vcc, v201, v169
	v_mul_f32_e32 v230, v153, v216
	v_fma_f32 v216, v153, v216, v203
	s_and_b64 vcc, s[38:39], vcc
	v_cndmask_b32_e32 v230, v230, v216, vcc
	v_add_u32_e32 v216, 0x46, v180
	v_cvt_pk_bf16_f32 v230, v179, v230
	s_nop 0
	s_nop 1
	v_cmp_le_i32_e32 vcc, v216, v169
	v_cmp_eq_u32_e64 s[100:101], v216, v169
	s_xnor_b64 vcc, vcc, s[38:39]
	s_or_b64 vcc, vcc, s[100:101]
	v_cndmask_b32_e32 v231, 0, v233, vcc
	v_mul_f32_e32 v217, v231, v217
	v_cmp_eq_u32_e32 vcc, v216, v169
	v_mul_f32_e32 v231, v154, v217
	v_fma_f32 v217, v154, v217, v203
	s_and_b64 vcc, s[38:39], vcc
	v_cndmask_b32_e32 v231, v231, v217, vcc
	v_add_u32_e32 v217, 0x47, v180
	s_nop 1
	s_nop 1
	v_cmp_le_i32_e32 vcc, v217, v169
	v_cmp_eq_u32_e64 s[100:101], v217, v169
	s_xnor_b64 vcc, vcc, s[38:39]
	s_or_b64 vcc, vcc, s[100:101]
	v_cndmask_b32_e32 v232, 0, v234, vcc
	v_mul_f32_e32 v218, v232, v218
	v_cmp_eq_u32_e32 vcc, v217, v169
	v_mul_f32_e32 v232, v155, v218
	v_fma_f32 v218, v155, v218, v203
	s_and_b64 vcc, s[38:39], vcc
	v_cndmask_b32_e32 v218, v232, v218, vcc
	v_cvt_pk_bf16_f32 v231, v231, v218
	v_add_u32_e32 v218, s5, v169
	v_ashrrev_i32_e32 v219, 31, v218
	v_mfma_f32_16x16x32_bf16 v[232:235], v[100:103], v[228:231], v[148:151]
	v_lshlrev_b64 v[218:219], 13, v[218:219]
	v_lshl_add_u64 v[218:219], v[198:199], 0, v[218:219]
	v_or_b32_e32 v169, 0x50, v176
	s_waitcnt vmcnt(5)
	v_mfma_f32_16x16x32_bf16 v[144:147], v[140:143], v[228:231], v[144:147]
	v_mov_b64_e32 v[150:151], s[94:95]
	s_nop 2
	v_pk_fma_f32 v[226:227], v[170:171], v[226:227], v[234:235] op_sel_hi:[0,1,1]
	v_pk_fma_f32 v[224:225], v[170:171], v[224:225], v[232:233] op_sel_hi:[0,1,1]
	v_cvt_pk_bf16_f32 v224, v224, v225
	v_cvt_pk_bf16_f32 v225, v226, v227
	v_pk_fma_f32 v[146:147], v[170:171], v[222:223], v[146:147] op_sel_hi:[0,1,1]
	v_pk_fma_f32 v[144:145], v[170:171], v[220:221], v[144:145] op_sel_hi:[0,1,1]
	v_cvt_pk_bf16_f32 v144, v144, v145
	v_cvt_pk_bf16_f32 v145, v146, v147
	global_store_dwordx2 v[218:219], v[224:225], off
	global_store_dwordx2 v[218:219], v[144:145], off offset:32
	v_lshlrev_b32_e32 v218, 8, v169
	v_mov_b64_e32 v[146:147], s[94:95]
	v_mov_b64_e32 v[148:149], s[92:93]
	v_add_u32_e32 v170, s87, v218
	s_and_b64 vcc, exec, s[46:47]
	v_mov_b64_e32 v[144:145], s[92:93]
	s_cbranch_vccz .LBB0_534
	s_and_b64 vcc, exec, s[46:47]
	s_cbranch_vccz .LBB0_535

; #define LAS __attribute__((address_space(3)))
; template <int MODE> __device__ __forceinline__ void ssd_scan_phase(Frame& F, int j, bool ctx_out) {
;     ...
;                 for (int lt = 0; lt < 8; ++lt) {
;                     const int l = 16 * lt + fr; const float cl = tab[l];
;                     f32x4 accd[2], acco[2];
;                     accd[0] = accd[1] = acco[0] = acco[1] = (f32x4){0.f, 0.f, 0.f, 0.f};
;                     const int kd = lt >> 1;
;                     if ((lt & 1) == 0) { xb_cur = xb_nxt; if (kd + 1 < 4) xb_nxt = *(const bf16x8*)(xl + (size_t)16 * T + 32 * (kd + 1)); }
;                     const bf16x8 xa = xf[0][kd], xb = xb_cur;
; #pragma unroll
;                     for (int ks = 0; ks < 4; ++ks) {
;                         const bool full = dir == 0 ? (ks < kd) : (ks > kd);
;                         if (full) {
;                             const bf16x8 gf = *(const LAS bf16x8*)(GS + l * 256 + (((4 * ks + fq) ^ fr) << 4));
;                             const float f1 = __builtin_amdgcn_exp2f(cl - tab[dir == 0 ? 32 * ks + 31 : 32 * ks]);
;                             const f32x4 z4 = (f32x4){0.f, 0.f, 0.f, 0.f};
;                             const f32x4 t0 = __builtin_amdgcn_mfma_f32_16x16x32_bf16(xs2[0][ks], gf, z4, 0, 0, 0), t1 = __builtin_amdgcn_mfma_f32_16x16x32_bf16(xs2[1][ks], gf, z4, 0, 0, 0);
;                             accd[0] += t0 * f1; accd[1] += t1 * f1;
;                         }
;                     }
; #pragma unroll
;                     for (int q = 0; q < 4; ++q) {
;                         const u32x2 lo = *(const LAS u32x2*)(CS + l * 256 + (((4 * q + (fq >> 1)) ^ fr) << 4) + (fq & 1) * 8), hi = *(const LAS u32x2*)(CS + l * 256 + (((4 * q + 2 + (fq >> 1)) ^ fr) << 4) + (fq & 1) * 8);
;                         u32x4 c4; c4.x = lo.x; c4.y = lo.y; c4.z = hi.x; c4.w = hi.y; const bf16x8 cfr = __builtin_bit_cast(bf16x8, c4);
;                         acco[0] = __builtin_amdgcn_mfma_f32_16x16x32_bf16(hf[0][q], cfr, acco[0], 0, 0, 0);
;                         acco[1] = __builtin_amdgcn_mfma_f32_16x16x32_bf16(hf[1][q], cfr, acco[1], 0, 0, 0);
;                     }
;     ...
;                 dtr0 = dtb[(size_t)(row0n + lane) * 128 + dir * 64 + h]; dtr1 = dtb[(size_t)(row0n + 64 + lane) * 128 + dir * 64 + h];
.LBB0_514:
	v_mbcnt_lo_u32_b32 v179, -1, 0
	v_mbcnt_hi_u32_b32 v179, -1, v179
	s_sub_i32 s100, s4, 1
	s_sub_i32 s101, 16, s4
	s_cmp_lg_u32 s38, 0
	s_cselect_b32 s100, s100, s101
	v_and_b32_e32 v178, 3, v179
	s_lshl_b32 s100, s100, 7
	s_add_i32 s100, s100, s81
	s_cmp_eq_u32 s4, 0
	s_cselect_b32 s100, s76, s100
	s_cmp_eq_u32 s4, 17
	s_cselect_b32 s100, s81, s100
	v_lshl_add_u32 v178, v178, 5, v188
	v_and_b32_e32 v179, 4, v179
	s_lshl_b32 s100, s100, 11
	v_lshlrev_b32_e32 v178, 11, v178
	v_lshl_add_u32 v178, v179, 5, v178
	s_mov_b32 m0, 0x1c000
	v_add_u32_e32 v178, s100, v178
	s_mov_b32 s100, s77
	s_mov_b32 s101, s73
	global_load_lds_dword v178, s[100:101]
	global_load_lds_dword v178, s[74:75]
	v_add3_u32 v178, 0, v218, v195
	v_add_u32_e32 v179, v178, v185
	ds_read_b64 v[218:219], v179
	v_add_u32_e32 v179, v178, v183
	ds_read_b64 v[220:221], v179
	v_add_u32_e32 v179, v178, v187
	ds_read_b64 v[226:227], v179
	v_add_u32_e32 v179, v178, v213
	ds_read_b64 v[228:229], v179
	s_waitcnt lgkmcnt(2)
	v_mfma_f32_16x16x32_bf16 v[222:225], v[116:119], v[218:221], 0
	v_add_u32_e32 v179, v178, v212
	ds_read_b64 v[230:231], v179
	v_add_u32_e32 v179, v178, v211
	v_mfma_f32_16x16x32_bf16 v[218:221], v[124:127], v[218:221], 0
	ds_read_b64 v[232:233], v179
	v_add_u32_e32 v179, v178, v191
	v_add_u32_e32 v178, v178, v210
	s_waitcnt lgkmcnt(2)
	v_mfma_f32_16x16x32_bf16 v[222:225], v[112:115], v[226:229], v[222:225]
	v_add_u32_e32 v170, v170, v168
	v_sub_f32_e32 v164, v171, v164
	v_exp_f32_e32 v164, v164
	v_mfma_f32_16x16x32_bf16 v[218:221], v[120:123], v[226:229], v[218:221]
	ds_read_b64 v[226:227], v179
	ds_read_b64 v[228:229], v178
	v_sub_f32_e32 v165, v171, v165
	s_waitcnt lgkmcnt(2)
	v_mfma_f32_16x16x32_bf16 v[222:225], v[108:111], v[230:233], v[222:225]
	v_exp_f32_e32 v165, v165
	v_sub_f32_e32 v166, v171, v166
	v_exp_f32_e32 v166, v166
	v_mfma_f32_16x16x32_bf16 v[218:221], v[128:131], v[230:233], v[218:221]
	ds_read_b128 v[230:233], v170
	v_add_u32_e32 v170, 64, v180
	s_waitcnt lgkmcnt(1)
	v_mfma_f32_16x16x32_bf16 v[222:225], v[104:107], v[226:229], v[222:225]
	s_waitcnt lgkmcnt(0)
; #define LAS __attribute__((address_space(3)))
; __device__ __forceinline__ unsigned cvt_pk_bf16(float lo, float hi) { const f32x2 v = {lo, hi}; return __builtin_bit_cast(unsigned, __builtin_convertvector(v, bf16x2_t)); }
; __device__ __forceinline__ u32x4 pack8(const float (&f)[8]) { u32x4 w; w.x = cvt_pk_bf16(f[0], f[1]); w.y = cvt_pk_bf16(f[2], f[3]); w.z = cvt_pk_bf16(f[4], f[5]); w.w = cvt_pk_bf16(f[6], f[7]); return w; }
; template <int MODE> __device__ __forceinline__ void ssd_scan_phase(Frame& F, int j, bool ctx_out) {
;     ...
;                         float gg[8]; unpack8(*(const LAS u32x4*)(GS + l * 256 + (((4 * kd + fq) ^ fr) << 4)), gg);
;                         const f32x4 ca = *(const LAS f32x4*)(tab + 32 * kd + 8 * fq), cb = *(const LAS f32x4*)(tab + 32 * kd + 8 * fq + 4);
;                         const f32x4 da = *(const LAS f32x4*)(tab + 128 + 32 * kd + 8 * fq), db = *(const LAS f32x4*)(tab + 128 + 32 * kd + 8 * fq + 4);
;                         const float cs[8] = {ca.x, ca.y, ca.z, ca.w, cb.x, cb.y, cb.z, cb.w}, ds[8] = {da.x, da.y, da.z, da.w, db.x, db.y, db.z, db.w};
;                         float m[8];
; #pragma unroll
;                         for (int jj = 0; jj < 8; ++jj) { const int s = 32 * kd + 8 * fq + jj; const bool valid = dir == 0 ? (s <= l) : (s >= l);
;                             const float e = valid ? __builtin_amdgcn_exp2f(cl - cs[jj]) : 0.f; m[jj] = gg[jj] * e * ds[jj]; if (dir == 0 && s == l) m[jj] += dsk; }
;                         const bf16x8 mf = __builtin_bit_cast(bf16x8, pack8(m));
;                         accd[0] = __builtin_amdgcn_mfma_f32_16x16x32_bf16(xa, mf, accd[0], 0, 0, 0);
;                         accd[1] = __builtin_amdgcn_mfma_f32_16x16x32_bf16(xb, mf, accd[1], 0, 0, 0);
;                     }
;                     const float el = __builtin_amdgcn_exp2f(cl);
; #pragma unroll
;                     for (int pt = 0; pt < 2; ++pt) { const f32x4 y = accd[pt] + acco[pt] * el; u32x2 o; o.x = cvt_pk_bf16(y[0], y[1]); o.y = cvt_pk_bf16(y[2], y[3]);
;                         *(u32x2*)(yout + (size_t)(row0 + l) * DI + h * 64 + ph * 32 + 16 * pt + 4 * fq) = o; }
	v_lshlrev_b32_e32 v178, 16, v230
	v_and_b32_e32 v179, 0xffff0000, v230
	v_lshlrev_b32_e32 v230, 16, v233
	v_mfma_f32_16x16x32_bf16 v[218:221], v[132:135], v[226:229], v[218:221]
	v_lshlrev_b32_e32 v226, 16, v231
	v_and_b32_e32 v227, 0xffff0000, v231
	v_lshlrev_b32_e32 v228, 16, v232
	v_and_b32_e32 v229, 0xffff0000, v232
	v_and_b32_e32 v231, 0xffff0000, v233
	v_cmp_le_i32_e32 vcc, v170, v169
	v_cmp_eq_u32_e64 s[100:101], v170, v169
	s_xnor_b64 vcc, vcc, s[38:39]
	s_or_b64 vcc, vcc, s[100:101]
	v_sub_f32_e32 v156, v171, v156
	v_cndmask_b32_e32 v164, 0, v164, vcc
	v_mul_f32_e32 v164, v164, v178
	v_cmp_eq_u32_e32 vcc, v170, v169
	v_mul_f32_e32 v178, v160, v164
	s_and_b64 vcc, s[38:39], vcc
	v_fma_f32 v160, v160, v164, v203
	v_cndmask_b32_e32 v160, v178, v160, vcc
	v_cmp_le_i32_e32 vcc, v173, v169
	v_cmp_eq_u32_e64 s[100:101], v173, v169
	s_xnor_b64 vcc, vcc, s[38:39]
	s_or_b64 vcc, vcc, s[100:101]
	v_exp_f32_e32 v156, v156
	v_sub_f32_e32 v157, v171, v157
	v_cndmask_b32_e32 v164, 0, v165, vcc
	v_mul_f32_e32 v164, v164, v179
	v_cmp_eq_u32_e32 vcc, v173, v169
	v_mul_f32_e32 v165, v161, v164
	s_and_b64 vcc, s[38:39], vcc
	v_fma_f32 v161, v161, v164, v203
	v_cndmask_b32_e32 v161, v165, v161, vcc
	v_cmp_le_i32_e32 vcc, v174, v169
	v_cmp_eq_u32_e64 s[100:101], v174, v169
	s_xnor_b64 vcc, vcc, s[38:39]
	s_or_b64 vcc, vcc, s[100:101]
	v_exp_f32_e32 v157, v157
	v_sub_f32_e32 v158, v171, v158
	v_cndmask_b32_e32 v164, 0, v166, vcc
	v_mul_f32_e32 v164, v164, v226
	v_cmp_eq_u32_e32 vcc, v174, v169
	v_mul_f32_e32 v165, v162, v164
	s_and_b64 vcc, s[38:39], vcc
	v_fma_f32 v162, v162, v164, v203
	v_cndmask_b32_e32 v162, v165, v162, vcc
	v_sub_f32_e32 v166, v171, v167
	v_exp_f32_e32 v166, v166
	v_cmp_le_i32_e32 vcc, v175, v169
	v_cmp_eq_u32_e64 s[100:101], v175, v169
	s_xnor_b64 vcc, vcc, s[38:39]
	s_or_b64 vcc, vcc, s[100:101]
	v_exp_f32_e32 v158, v158
	v_cndmask_b32_e32 v164, 0, v166, vcc
	v_mul_f32_e32 v164, v164, v227
	v_cmp_eq_u32_e32 vcc, v175, v169
	v_mul_f32_e32 v165, v163, v164
	s_and_b64 vcc, s[38:39], vcc
	v_fma_f32 v163, v163, v164, v203
	v_cndmask_b32_e32 v163, v165, v163, vcc
	v_cmp_le_i32_e32 vcc, v200, v169
	v_cmp_eq_u32_e64 s[100:101], v200, v169
	s_xnor_b64 vcc, vcc, s[38:39]
	s_or_b64 vcc, vcc, s[100:101]
	s_mov_b32 s94, s92
	s_mov_b32 s95, s92
	v_cndmask_b32_e32 v156, 0, v156, vcc
	v_mul_f32_e32 v156, v156, v228
	v_cmp_eq_u32_e32 vcc, v200, v169
	v_mul_f32_e32 v164, v152, v156
	s_and_b64 vcc, s[38:39], vcc
	v_fma_f32 v152, v152, v156, v203
	v_cndmask_b32_e32 v156, v164, v152, vcc
	v_cmp_le_i32_e32 vcc, v201, v169
	v_cmp_eq_u32_e64 s[100:101], v201, v169
	s_xnor_b64 vcc, vcc, s[38:39]
	s_or_b64 vcc, vcc, s[100:101]
	s_mov_b32 s93, s92
	s_nop 0
	v_cndmask_b32_e32 v152, 0, v157, vcc
	v_mul_f32_e32 v152, v152, v229
	v_cmp_eq_u32_e32 vcc, v201, v169
	v_mul_f32_e32 v157, v153, v152
	s_and_b64 vcc, s[38:39], vcc
	v_fma_f32 v152, v153, v152, v203
	v_cndmask_b32_e32 v157, v157, v152, vcc
	v_cmp_le_i32_e32 vcc, v216, v169
	v_cmp_eq_u32_e64 s[100:101], v216, v169
	s_xnor_b64 vcc, vcc, s[38:39]
	s_or_b64 vcc, vcc, s[100:101]
	v_cndmask_b32_e32 v152, 0, v158, vcc
	v_mul_f32_e32 v152, v152, v230
	v_cmp_eq_u32_e32 vcc, v216, v169
	v_mul_f32_e32 v153, v154, v152
	s_and_b64 vcc, s[38:39], vcc
	v_fma_f32 v152, v154, v152, v203
	v_cndmask_b32_e32 v158, v153, v152, vcc
	v_sub_f32_e32 v154, v171, v159
	v_exp_f32_e32 v154, v154
	v_cmp_le_i32_e32 vcc, v217, v169
	v_cmp_eq_u32_e64 s[100:101], v217, v169
	s_xnor_b64 vcc, vcc, s[38:39]
	s_or_b64 vcc, vcc, s[100:101]
	v_cndmask_b32_e32 v152, 0, v154, vcc
	v_mul_f32_e32 v152, v152, v231
	v_cmp_eq_u32_e32 vcc, v217, v169
	v_mul_f32_e32 v153, v155, v152
	s_and_b64 vcc, s[38:39], vcc
	v_fma_f32 v152, v155, v152, v203
	v_cndmask_b32_e32 v155, v153, v152, vcc
	v_cvt_pk_bf16_f32 v152, v160, v161
	v_cvt_pk_bf16_f32 v153, v162, v163
	v_cvt_pk_bf16_f32 v154, v156, v157
	v_cvt_pk_bf16_f32 v155, v158, v155
	ds_read_b32 v161, v214 offset:384
	v_or_b32_e32 v160, 0x60, v176
	v_mfma_f32_16x16x32_bf16 v[144:147], v[100:103], v[152:155], v[144:147]
	v_mov_b64_e32 v[102:103], s[94:95]
	v_mov_b64_e32 v[100:101], s[92:93]
	s_and_b64 vcc, exec, s[46:47]
	v_mfma_f32_16x16x32_bf16 v[140:143], v[140:143], v[152:155], v[148:151]
	s_nop 2
	v_exp_f32_e32 v148, v171
	v_add_u32_e32 v150, s5, v169
	v_ashrrev_i32_e32 v151, 31, v150
	v_lshlrev_b64 v[150:151], 13, v[150:151]
	v_pk_fma_f32 v[146:147], v[148:149], v[224:225], v[146:147] op_sel_hi:[0,1,1]
	v_pk_fma_f32 v[144:145], v[148:149], v[222:223], v[144:145] op_sel_hi:[0,1,1]
	v_pk_fma_f32 v[142:143], v[148:149], v[220:221], v[142:143] op_sel_hi:[0,1,1]
	v_pk_fma_f32 v[140:141], v[148:149], v[218:219], v[140:141] op_sel_hi:[0,1,1]
	v_lshl_add_u64 v[150:151], v[198:199], 0, v[150:151]
	v_cvt_pk_bf16_f32 v144, v144, v145
	v_cvt_pk_bf16_f32 v145, v146, v147
	v_cvt_pk_bf16_f32 v140, v140, v141
	v_cvt_pk_bf16_f32 v141, v142, v143
	global_store_dwordx2 v[150:151], v[144:145], off
	global_store_dwordx2 v[150:151], v[140:141], off offset:32
	v_lshlrev_b32_e32 v141, 8, v160
	v_mov_b64_e32 v[150:151], s[94:95]
	v_add_u32_e32 v140, s87, v141
	v_mov_b64_e32 v[148:149], s[92:93]
	s_cbranch_vccz .LBB0_536
	s_and_b64 vcc, exec, s[46:47]
	s_cbranch_vccz .LBB0_537

; template <int MODE> __device__ __forceinline__ void ssd_scan_phase(Frame& F, int j, bool ctx_out) {
;     ...
;                 for (int lt = 0; lt < 8; ++lt) {
;                     const int l = 16 * lt + fr; const float cl = tab[l];
;                     f32x4 accd[2], acco[2];
;                     accd[0] = accd[1] = acco[0] = acco[1] = (f32x4){0.f, 0.f, 0.f, 0.f};
;                     const int kd = lt >> 1;
;                     if ((lt & 1) == 0) { xb_cur = xb_nxt; if (kd + 1 < 4) xb_nxt = *(const bf16x8*)(xl + (size_t)16 * T + 32 * (kd + 1)); }
;                     const bf16x8 xa = xf[0][kd], xb = xb_cur;
; #pragma unroll
;                     for (int ks = 0; ks < 4; ++ks) {
;                         const bool full = dir == 0 ? (ks < kd) : (ks > kd);
;                         if (full) {
;                             const bf16x8 gf = *(const LAS bf16x8*)(GS + l * 256 + (((4 * ks + fq) ^ fr) << 4));
;                             const float f1 = __builtin_amdgcn_exp2f(cl - tab[dir == 0 ? 32 * ks + 31 : 32 * ks]);
;                             const f32x4 z4 = (f32x4){0.f, 0.f, 0.f, 0.f};
;                             const f32x4 t0 = __builtin_amdgcn_mfma_f32_16x16x32_bf16(xs2[0][ks], gf, z4, 0, 0, 0), t1 = __builtin_amdgcn_mfma_f32_16x16x32_bf16(xs2[1][ks], gf, z4, 0, 0, 0);
;                             accd[0] += t0 * f1; accd[1] += t1 * f1;
;                         }
;                     }
; #pragma unroll
;                     for (int q = 0; q < 4; ++q) {
;                         const u32x2 lo = *(const LAS u32x2*)(CS + l * 256 + (((4 * q + (fq >> 1)) ^ fr) << 4) + (fq & 1) * 8), hi = *(const LAS u32x2*)(CS + l * 256 + (((4 * q + 2 + (fq >> 1)) ^ fr) << 4) + (fq & 1) * 8);
;                         u32x4 c4; c4.x = lo.x; c4.y = lo.y; c4.z = hi.x; c4.w = hi.y; const bf16x8 cfr = __builtin_bit_cast(bf16x8, c4);
;                         acco[0] = __builtin_amdgcn_mfma_f32_16x16x32_bf16(hf[0][q], cfr, acco[0], 0, 0, 0);
;                         acco[1] = __builtin_amdgcn_mfma_f32_16x16x32_bf16(hf[1][q], cfr, acco[1], 0, 0, 0);
;                     }
;                     {
;                         float gg[8]; unpack8(*(const LAS u32x4*)(GS + l * 256 + (((4 * kd + fq) ^ fr) << 4)), gg);
;                         const f32x4 ca = *(const LAS f32x4*)(tab + 32 * kd + 8 * fq), cb = *(const LAS f32x4*)(tab + 32 * kd + 8 * fq + 4);
.LBB0_518:
	v_add3_u32 v141, 0, v141, v195
	v_add_u32_e32 v142, v141, v185
	v_add_u32_e32 v144, v141, v183
	ds_read_b64 v[142:143], v142
	ds_read_b64 v[144:145], v144
	v_add_u32_e32 v146, v141, v187
	ds_read_b64 v[152:153], v146
	ds_read_b32 v162, v214 offset:448
	v_add_u32_e32 v146, v141, v213
	ds_read_b64 v[154:155], v146
	s_waitcnt lgkmcnt(3)
	v_mfma_f32_16x16x32_bf16 v[156:159], v[116:119], v[142:145], 0
	v_add_u32_e32 v146, v141, v212
	v_add_u32_e32 v147, v141, v211
	v_add_u32_e32 v163, v141, v191
	v_mfma_f32_16x16x32_bf16 v[142:145], v[124:127], v[142:145], 0
	ds_read_b64 v[164:165], v146
	ds_read_b64 v[166:167], v147
	ds_read_b64 v[216:217], v163
	v_add_u32_e32 v141, v141, v210
	v_lshlrev_b32_e32 v171, 4, v205
	s_waitcnt lgkmcnt(3)
	v_mfma_f32_16x16x32_bf16 v[156:159], v[112:115], v[152:155], v[156:159]
	ds_read_b64 v[218:219], v141
	v_add_u32_e32 v140, v140, v171
	v_add_u32_e32 v170, 0x61, v180
	v_mfma_f32_16x16x32_bf16 v[142:145], v[120:123], v[152:155], v[142:145]
	v_add_u32_e32 v169, 0x62, v180
	s_mov_b32 s94, s92
	s_waitcnt lgkmcnt(2)
	v_mfma_f32_16x16x32_bf16 v[152:155], v[108:111], v[164:167], v[156:159]
	s_mov_b32 s95, s92
	s_mov_b32 s93, s92
	s_nop 0
	ds_read_b128 v[156:159], v197 offset:384
	v_mfma_f32_16x16x32_bf16 v[142:145], v[128:131], v[164:167], v[142:145]
	ds_read_b128 v[164:167], v140
	s_waitcnt lgkmcnt(1)
	v_sub_f32_e32 v140, v161, v156
	v_mfma_f32_16x16x32_bf16 v[220:223], v[104:107], v[216:219], v[152:155]
	s_waitcnt lgkmcnt(0)
	v_lshlrev_b32_e32 v174, 16, v166
	v_and_b32_e32 v175, 0xffff0000, v166
	v_exp_f32_e32 v166, v140
	v_mfma_f32_16x16x32_bf16 v[216:219], v[132:135], v[216:219], v[142:145]
	ds_read_b128 v[152:155], v197 offset:896
	v_lshlrev_b32_e32 v163, 16, v164
	v_cndmask_b32_e64 v166, 0, v166, s[40:41]
	ds_read_b128 v[144:147], v197 offset:400
	v_mul_f32_e32 v163, v166, v163
	s_waitcnt lgkmcnt(1)
	v_mul_f32_e32 v166, v152, v163
	v_fma_f32 v163, v152, v163, v203
	v_lshlrev_b32_e32 v178, 16, v167
	v_and_b32_e32 v179, 0xffff0000, v167
	ds_read_b128 v[140:143], v197 offset:912
	v_cndmask_b32_e64 v197, v166, v163, s[42:43]
	v_sub_f32_e32 v167, v161, v157
	v_exp_f32_e32 v167, v167
	v_cmp_le_i32_e32 vcc, v170, v160
	v_cmp_eq_u32_e64 s[100:101], v170, v160
	s_xnor_b64 vcc, vcc, s[38:39]
	s_or_b64 vcc, vcc, s[100:101]
	v_and_b32_e32 v164, 0xffff0000, v164
	v_sub_f32_e32 v166, v161, v158
	v_cndmask_b32_e32 v163, 0, v167, vcc
	v_mul_f32_e32 v163, v163, v164
	v_cmp_eq_u32_e32 vcc, v170, v160
	v_mul_f32_e32 v164, v153, v163
	v_fma_f32 v163, v153, v163, v203
	s_and_b64 vcc, s[38:39], vcc
	v_cndmask_b32_e32 v200, v164, v163, vcc
	v_exp_f32_e32 v166, v166
	v_lshlrev_b32_e32 v173, 16, v165
	v_add_u32_e32 v167, 0x63, v180
	v_and_b32_e32 v165, 0xffff0000, v165
	v_cmp_le_i32_e32 vcc, v169, v160
	v_cmp_eq_u32_e64 s[100:101], v169, v160
	s_xnor_b64 vcc, vcc, s[38:39]
	s_or_b64 vcc, vcc, s[100:101]
	s_waitcnt lgkmcnt(1)
	v_sub_f32_e32 v214, v161, v145
	v_exp_f32_e32 v214, v214
	v_cndmask_b32_e32 v163, 0, v166, vcc
	v_mul_f32_e32 v163, v163, v173
	v_cmp_eq_u32_e32 vcc, v169, v160
	v_mul_f32_e32 v164, v154, v163
	v_fma_f32 v163, v154, v163, v203
	s_and_b64 vcc, s[38:39], vcc
	v_cndmask_b32_e32 v173, v164, v163, vcc
	v_sub_f32_e32 v166, v161, v159
	v_exp_f32_e32 v166, v166
	v_sub_f32_e32 v224, v161, v146
	v_exp_f32_e32 v224, v224
	v_cmp_le_i32_e32 vcc, v167, v160
	v_cmp_eq_u32_e64 s[100:101], v167, v160
	s_xnor_b64 vcc, vcc, s[38:39]
	s_or_b64 vcc, vcc, s[100:101]
	v_sub_f32_e32 v225, v161, v147
	v_exp_f32_e32 v225, v225
	v_cndmask_b32_e32 v163, 0, v166, vcc
	v_mul_f32_e32 v163, v163, v165
	v_cmp_eq_u32_e32 vcc, v167, v160
	v_mul_f32_e32 v164, v155, v163
	v_fma_f32 v163, v155, v163, v203
	s_and_b64 vcc, s[38:39], vcc
	v_add_u32_e32 v166, 0x64, v180
	v_cndmask_b32_e32 v201, v164, v163, vcc
	v_sub_f32_e32 v165, v161, v144
	v_exp_f32_e32 v165, v165
	s_nop 1
	v_cmp_le_i32_e32 vcc, v166, v160
	v_cmp_eq_u32_e64 s[100:101], v166, v160
	s_xnor_b64 vcc, vcc, s[38:39]
	s_or_b64 vcc, vcc, s[100:101]
	v_cndmask_b32_e32 v163, 0, v165, vcc
	v_mul_f32_e32 v163, v163, v174
	v_cmp_eq_u32_e32 vcc, v166, v160
	s_waitcnt lgkmcnt(0)
	v_mul_f32_e32 v164, v140, v163
	v_fma_f32 v163, v140, v163, v203
	s_and_b64 vcc, s[38:39], vcc
	v_add_u32_e32 v165, 0x65, v180
	v_cndmask_b32_e32 v174, v164, v163, vcc
	s_nop 1
	s_nop 1
	v_cmp_le_i32_e32 vcc, v165, v160
	v_cmp_eq_u32_e64 s[100:101], v165, v160
	s_xnor_b64 vcc, vcc, s[38:39]
	s_or_b64 vcc, vcc, s[100:101]
	v_cndmask_b32_e32 v163, 0, v214, vcc
	v_mul_f32_e32 v163, v163, v175
	v_cmp_eq_u32_e32 vcc, v165, v160
	v_mul_f32_e32 v164, v141, v163
	v_fma_f32 v163, v141, v163, v203
	s_and_b64 vcc, s[38:39], vcc
	v_cndmask_b32_e32 v175, v164, v163, vcc
	v_add_u32_e32 v164, 0x66, v180
	v_cvt_pk_bf16_f32 v226, v174, v175
	v_exp_f32_e32 v174, v161
	s_nop 1
	v_cmp_le_i32_e32 vcc, v164, v160
	v_cmp_eq_u32_e64 s[100:101], v164, v160
	s_xnor_b64 vcc, vcc, s[38:39]
	s_or_b64 vcc, vcc, s[100:101]
	v_cndmask_b32_e32 v163, 0, v224, vcc
	v_mul_f32_e32 v163, v163, v178
	v_cmp_eq_u32_e32 vcc, v164, v160
	v_mul_f32_e32 v178, v142, v163
	v_fma_f32 v163, v142, v163, v203
	s_and_b64 vcc, s[38:39], vcc
	v_cndmask_b32_e32 v178, v178, v163, vcc
	v_add_u32_e32 v163, 0x67, v180
	s_nop 1
	s_nop 1
	v_cmp_le_i32_e32 vcc, v163, v160
	v_cmp_eq_u32_e64 s[100:101], v163, v160
	s_xnor_b64 vcc, vcc, s[38:39]
	s_or_b64 vcc, vcc, s[100:101]
	v_cvt_pk_bf16_f32 v224, v197, v200
	s_nop 0
	v_cndmask_b32_e32 v214, 0, v225, vcc
	v_mul_f32_e32 v179, v214, v179
	v_cmp_eq_u32_e32 vcc, v163, v160
	v_mul_f32_e32 v214, v143, v179
	v_fma_f32 v179, v143, v179, v203
	s_and_b64 vcc, s[38:39], vcc
	v_cndmask_b32_e32 v179, v214, v179, vcc
	v_cvt_pk_bf16_f32 v225, v173, v201
	v_cvt_pk_bf16_f32 v227, v178, v179
	v_add_u32_e32 v160, s5, v160
	v_ashrrev_i32_e32 v161, 31, v160
	v_mfma_f32_16x16x32_bf16 v[228:231], v[8:11], v[224:227], v[148:151]
	v_lshlrev_b64 v[160:161], 13, v[160:161]
	v_lshl_add_u64 v[160:161], v[198:199], 0, v[160:161]
	s_and_b64 vcc, exec, s[46:47]
	s_waitcnt vmcnt(6)
	v_mfma_f32_16x16x32_bf16 v[100:103], v[136:139], v[224:227], v[100:103]
	v_mov_b64_e32 v[150:151], s[94:95]
	s_nop 1
	v_pk_fma_f32 v[200:201], v[174:175], v[222:223], v[230:231] op_sel_hi:[0,1,1]
	v_pk_fma_f32 v[220:221], v[174:175], v[220:221], v[228:229] op_sel_hi:[0,1,1]
	v_cvt_pk_bf16_f32 v220, v220, v221
	v_cvt_pk_bf16_f32 v221, v200, v201
	s_nop 0
	v_pk_fma_f32 v[102:103], v[174:175], v[218:219], v[102:103] op_sel_hi:[0,1,1]
	v_pk_fma_f32 v[100:101], v[174:175], v[216:217], v[100:101] op_sel_hi:[0,1,1]
	v_cvt_pk_bf16_f32 v100, v100, v101
	v_cvt_pk_bf16_f32 v101, v102, v103
	global_store_dwordx2 v[160:161], v[220:221], off
	global_store_dwordx2 v[160:161], v[100:101], off offset:32
	v_or_b32_e32 v160, 0x70, v176
	v_lshlrev_b32_e32 v173, 8, v160
	v_mov_b64_e32 v[102:103], s[94:95]
	v_mov_b64_e32 v[148:149], s[92:93]
	v_add_u32_e32 v161, s87, v173
	v_mov_b64_e32 v[100:101], s[92:93]
	s_cbranch_vccz .LBB0_538
	s_and_b64 vcc, exec, s[46:47]
	s_cbranch_vccz .LBB0_539

; template <int MODE> __device__ __forceinline__ void ssd_scan_phase(Frame& F, int j, bool ctx_out) {
;     ...
;                 for (int lt = 0; lt < 8; ++lt) {
;                     const int l = 16 * lt + fr; const float cl = tab[l];
;                     f32x4 accd[2], acco[2];
;                     accd[0] = accd[1] = acco[0] = acco[1] = (f32x4){0.f, 0.f, 0.f, 0.f};
;                     const int kd = lt >> 1;
;                     if ((lt & 1) == 0) { xb_cur = xb_nxt; if (kd + 1 < 4) xb_nxt = *(const bf16x8*)(xl + (size_t)16 * T + 32 * (kd + 1)); }
;                     const bf16x8 xa = xf[0][kd], xb = xb_cur;
; #pragma unroll
;                     for (int ks = 0; ks < 4; ++ks) {
;                         const bool full = dir == 0 ? (ks < kd) : (ks > kd);
;                         if (full) {
;                             const bf16x8 gf = *(const LAS bf16x8*)(GS + l * 256 + (((4 * ks + fq) ^ fr) << 4));
;                             const float f1 = __builtin_amdgcn_exp2f(cl - tab[dir == 0 ? 32 * ks + 31 : 32 * ks]);
;                             const f32x4 z4 = (f32x4){0.f, 0.f, 0.f, 0.f};
;                             const f32x4 t0 = __builtin_amdgcn_mfma_f32_16x16x32_bf16(xs2[0][ks], gf, z4, 0, 0, 0), t1 = __builtin_amdgcn_mfma_f32_16x16x32_bf16(xs2[1][ks], gf, z4, 0, 0, 0);
;                             accd[0] += t0 * f1; accd[1] += t1 * f1;
;                         }
;                     }
; #pragma unroll
;                     for (int q = 0; q < 4; ++q) {
;                         const u32x2 lo = *(const LAS u32x2*)(CS + l * 256 + (((4 * q + (fq >> 1)) ^ fr) << 4) + (fq & 1) * 8), hi = *(const LAS u32x2*)(CS + l * 256 + (((4 * q + 2 + (fq >> 1)) ^ fr) << 4) + (fq & 1) * 8);
;                         u32x4 c4; c4.x = lo.x; c4.y = lo.y; c4.z = hi.x; c4.w = hi.y; const bf16x8 cfr = __builtin_bit_cast(bf16x8, c4);
;                         acco[0] = __builtin_amdgcn_mfma_f32_16x16x32_bf16(hf[0][q], cfr, acco[0], 0, 0, 0);
;                         acco[1] = __builtin_amdgcn_mfma_f32_16x16x32_bf16(hf[1][q], cfr, acco[1], 0, 0, 0);
;                     }
;                     {
;                         float gg[8]; unpack8(*(const LAS u32x4*)(GS + l * 256 + (((4 * kd + fq) ^ fr) << 4)), gg);
;                         const f32x4 ca = *(const LAS f32x4*)(tab + 32 * kd + 8 * fq), cb = *(const LAS f32x4*)(tab + 32 * kd + 8 * fq + 4);
.LBB0_522:
	v_add3_u32 v168, 0, v173, v195
	v_add_u32_e32 v172, v168, v185
	v_add_u32_e32 v174, v168, v183
	ds_read_b64 v[172:173], v172
	ds_read_b64 v[174:175], v174
	v_add_u32_e32 v178, v168, v187
	s_waitcnt lgkmcnt(0)
	v_mfma_f32_16x16x32_bf16 v[116:119], v[116:119], v[172:175], 0
	v_mfma_f32_16x16x32_bf16 v[124:127], v[124:127], v[172:175], 0
	v_add_u32_e32 v174, v168, v213
	ds_read_b64 v[172:173], v178
	ds_read_b64 v[174:175], v174
	s_waitcnt lgkmcnt(0)
	v_mfma_f32_16x16x32_bf16 v[112:115], v[112:115], v[172:175], v[116:119]
	s_nop 2
	v_add_u32_e32 v116, v168, v212
	v_add_u32_e32 v118, v168, v211
	ds_read_b64 v[116:117], v116
	ds_read_b64 v[118:119], v118
	v_mfma_f32_16x16x32_bf16 v[120:123], v[120:123], v[172:175], v[124:127]
	s_nop 2
	v_add_u32_e32 v124, v168, v191
	s_waitcnt lgkmcnt(0)
	v_mfma_f32_16x16x32_bf16 v[108:111], v[108:111], v[116:119], v[112:115]
	s_nop 2
	v_add_u32_e32 v114, v168, v210
	ds_read_b64 v[112:113], v124
	ds_read_b64 v[114:115], v114
	v_mfma_f32_16x16x32_bf16 v[116:119], v[128:131], v[116:119], v[120:123]
	v_add_u32_e32 v124, 0x60, v180
	v_add_u32_e32 v120, v161, v171
	ds_read_b128 v[120:123], v120
	s_waitcnt lgkmcnt(1)
	v_mfma_f32_16x16x32_bf16 v[108:111], v[104:107], v[112:115], v[108:111]
	s_waitcnt lgkmcnt(0)
	v_lshlrev_b32_e32 v125, 16, v120
	v_mfma_f32_16x16x32_bf16 v[104:107], v[132:135], v[112:115], v[116:119]
	v_lshlrev_b32_e32 v126, 16, v121
	v_and_b32_e32 v112, 0xffff0000, v121
	v_sub_f32_e32 v121, v162, v157
	v_sub_f32_e32 v119, v162, v156
	v_exp_f32_e32 v119, v119
	v_cmp_le_i32_e32 vcc, v124, v160
	v_cmp_eq_u32_e64 s[100:101], v124, v160
	s_xnor_b64 vcc, vcc, s[38:39]
	s_or_b64 vcc, vcc, s[100:101]
	v_exp_f32_e32 v121, v121
	v_cndmask_b32_e32 v117, 0, v119, vcc
	v_mul_f32_e32 v117, v117, v125
	v_cmp_eq_u32_e32 vcc, v124, v160
	v_mul_f32_e32 v118, v152, v117
	s_and_b64 vcc, s[38:39], vcc
	v_fma_f32 v117, v152, v117, v203
	v_cndmask_b32_e32 v117, v118, v117, vcc
	v_and_b32_e32 v120, 0xffff0000, v120
	v_cmp_le_i32_e32 vcc, v170, v160
	v_cmp_eq_u32_e64 s[100:101], v170, v160
	s_xnor_b64 vcc, vcc, s[38:39]
	s_or_b64 vcc, vcc, s[100:101]
	v_lshlrev_b32_e32 v113, 16, v122
	v_cndmask_b32_e32 v118, 0, v121, vcc
	v_mul_f32_e32 v118, v118, v120
	v_cmp_eq_u32_e32 vcc, v170, v160
	v_mul_f32_e32 v119, v153, v118
	s_and_b64 vcc, s[38:39], vcc
	v_fma_f32 v118, v153, v118, v203
	v_cndmask_b32_e32 v118, v119, v118, vcc
	v_sub_f32_e32 v121, v162, v158
	v_exp_f32_e32 v121, v121
	v_cmp_le_i32_e32 vcc, v169, v160
	v_cmp_eq_u32_e64 s[100:101], v169, v160
	s_xnor_b64 vcc, vcc, s[38:39]
	s_or_b64 vcc, vcc, s[100:101]
	v_and_b32_e32 v114, 0xffff0000, v122
	v_cndmask_b32_e32 v119, 0, v121, vcc
	v_mul_f32_e32 v119, v119, v126
	v_cmp_eq_u32_e32 vcc, v169, v160
	v_mul_f32_e32 v120, v154, v119
	s_and_b64 vcc, s[38:39], vcc
	v_fma_f32 v119, v154, v119, v203
	v_cndmask_b32_e32 v119, v120, v119, vcc
	v_sub_f32_e32 v122, v162, v159
	v_exp_f32_e32 v122, v122
	v_cmp_le_i32_e32 vcc, v167, v160
	v_cmp_eq_u32_e64 s[100:101], v167, v160
	s_xnor_b64 vcc, vcc, s[38:39]
	s_or_b64 vcc, vcc, s[100:101]
	v_lshlrev_b32_e32 v115, 16, v123
	v_cndmask_b32_e32 v120, 0, v122, vcc
	v_mul_f32_e32 v112, v120, v112
	v_cmp_eq_u32_e32 vcc, v167, v160
	v_mul_f32_e32 v120, v155, v112
	s_and_b64 vcc, s[38:39], vcc
	v_fma_f32 v112, v155, v112, v203
	v_cndmask_b32_e32 v120, v120, v112, vcc
	v_sub_f32_e32 v122, v162, v144
	v_exp_f32_e32 v122, v122
	v_cmp_le_i32_e32 vcc, v166, v160
	v_cmp_eq_u32_e64 s[100:101], v166, v160
	s_xnor_b64 vcc, vcc, s[38:39]
	s_or_b64 vcc, vcc, s[100:101]
	v_and_b32_e32 v116, 0xffff0000, v123
	v_cndmask_b32_e32 v112, 0, v122, vcc
	v_mul_f32_e32 v112, v112, v113
	v_cmp_eq_u32_e32 vcc, v166, v160
	v_mul_f32_e32 v113, v140, v112
	s_and_b64 vcc, s[38:39], vcc
	v_fma_f32 v112, v140, v112, v203
	v_cndmask_b32_e32 v121, v113, v112, vcc
	v_sub_f32_e32 v122, v162, v145
	v_exp_f32_e32 v122, v122
	v_cmp_le_i32_e32 vcc, v165, v160
	v_cmp_eq_u32_e64 s[100:101], v165, v160
	s_xnor_b64 vcc, vcc, s[38:39]
	s_or_b64 vcc, vcc, s[100:101]
	s_nop 0
	v_cndmask_b32_e32 v112, 0, v122, vcc
	v_mul_f32_e32 v112, v112, v114
	v_cmp_eq_u32_e32 vcc, v165, v160
	v_mul_f32_e32 v113, v141, v112
	s_and_b64 vcc, s[38:39], vcc
	v_fma_f32 v112, v141, v112, v203
	v_cndmask_b32_e32 v114, v113, v112, vcc
	v_sub_f32_e32 v122, v162, v146
	v_exp_f32_e32 v122, v122
	v_cmp_le_i32_e32 vcc, v164, v160
	v_cmp_eq_u32_e64 s[100:101], v164, v160
	s_xnor_b64 vcc, vcc, s[38:39]
	s_or_b64 vcc, vcc, s[100:101]
	v_cvt_pk_bf16_f32 v114, v121, v114
	v_cndmask_b32_e32 v112, 0, v122, vcc
	v_mul_f32_e32 v112, v112, v115
	v_cmp_eq_u32_e32 vcc, v164, v160
	v_mul_f32_e32 v113, v142, v112
	s_and_b64 vcc, s[38:39], vcc
	v_fma_f32 v112, v142, v112, v203
	v_cndmask_b32_e32 v115, v113, v112, vcc
	v_sub_f32_e32 v122, v162, v147
	v_exp_f32_e32 v122, v122
	v_cmp_le_i32_e32 vcc, v163, v160
	v_cmp_eq_u32_e64 s[100:101], v163, v160
	s_xnor_b64 vcc, vcc, s[38:39]
	s_or_b64 vcc, vcc, s[100:101]
	v_cndmask_b32_e32 v112, 0, v122, vcc
	v_mul_f32_e32 v112, v112, v116
	v_cmp_eq_u32_e32 vcc, v163, v160
	v_mul_f32_e32 v113, v143, v112
	s_and_b64 vcc, s[38:39], vcc
	v_fma_f32 v112, v143, v112, v203
	v_cndmask_b32_e32 v116, v113, v112, vcc
	v_cvt_pk_bf16_f32 v112, v117, v118
	v_cvt_pk_bf16_f32 v113, v119, v120
	v_cvt_pk_bf16_f32 v115, v115, v116
	s_nop 1
	v_mfma_f32_16x16x32_bf16 v[8:11], v[8:11], v[112:115], v[100:103]
	v_mfma_f32_16x16x32_bf16 v[100:103], v[136:139], v[112:115], v[148:151]
	v_exp_f32_e32 v112, v162
	v_add_u32_e32 v114, s5, v160
	v_ashrrev_i32_e32 v115, 31, v114
	v_lshlrev_b64 v[114:115], 13, v[114:115]
	s_nop 2
	v_pk_fma_f32 v[10:11], v[112:113], v[110:111], v[10:11] op_sel_hi:[0,1,1]
	v_pk_fma_f32 v[8:9], v[112:113], v[108:109], v[8:9] op_sel_hi:[0,1,1]
	v_lshl_add_u64 v[114:115], v[198:199], 0, v[114:115]
	v_cvt_pk_bf16_f32 v8, v8, v9
	v_cvt_pk_bf16_f32 v9, v10, v11
	global_store_dwordx2 v[114:115], v[8:9], off
	v_pk_fma_f32 v[8:9], v[112:113], v[106:107], v[102:103] op_sel_hi:[0,1,1]
	v_pk_fma_f32 v[10:11], v[112:113], v[104:105], v[100:101] op_sel_hi:[0,1,1]
	v_cvt_pk_bf16_f32 v10, v10, v11
	v_cvt_pk_bf16_f32 v11, v8, v9
	global_store_dwordx2 v[114:115], v[10:11], off offset:32
	s_branch .Lscan_b4_y
